# v092 + P10 v-sweep prologues: wait for the first row group moved to its first consumer, dead copies into v0-31 deleted
# baseline (speedup 1.0000x reference)
; __device__ __forceinline__ float gelu1(float x) { return 0.5f * x * (1.0f + erff(x * 0.70710678118654752f)); }
; #define PV_LOAD(BUF, EV, S0) do { _Pragma("unroll") for (int i = 0; i < 8; ++i) { const int row_ = __builtin_amdgcn_readlane(EV, (S0) + i); BUF[i & 3][i >> 2] = *(const u32x4*)(PV8 + (size_t)row_ * 1024 + lane * 16); } } while (0)
; __global__ void __launch_bounds__(NT, 2) mk_fwd(Args args) {
;     ...
;                 const float d = dv * SCL[ev];
;                 const float a = gelu1(d) * gv * SCL[16384 + ev];
;                 if (hh) act1 = a; else act0 = a;
;             }
;     ...
;             f32x2 acc2[16];
; #pragma unroll
;             for (int i = 0; i < 16; ++i) acc2[i] = (f32x2){0.f, 0.f};
;     ...
; #pragma unroll
;             for (int hh = 0; hh < 2; ++hh) {
;                 const int ev = hh ? e1 : e0; const float av = hh ? act1 : act0;
;                 PV_LOAD(bA, ev, 0);
; #pragma unroll 1
;                 for (int s = 0; s < 64; s += 16) {
;                     PV_LOAD(bB, ev, s + 8);
;                     PV_ACC(bA, av, s);
;                     if (s + 16 < 64) PV_LOAD(bA, ev, s + 16);
;                     PV_ACC(bB, av, s + 8);
.LBB0_902:
	s_andn2_saveexec_b64 s[4:5], s[4:5]
	v_mul_f32_e32 v2, v109, v109
	v_fmamk_f32 v3, v2, 0xba1345e1, v152
	v_fmaak_f32 v3, v2, v3, 0xbcdac9b8
	v_fmaak_f32 v3, v2, v3, 0x3de703be
	v_fmaak_f32 v3, v2, v3, 0xbec09330
	v_fmaak_f32 v2, v2, v3, 0x3e0375d0
	v_fma_f32 v157, |v109|, v2, |v109|
	s_or_b64 exec, exec, s[4:5]
	v_readlane_b32 s4, v108, 0
	s_ashr_i32 s5, s4, 31
	s_lshl_b64 s[4:5], s[4:5], 10
	v_lshl_add_u64 v[2:3], v[100:101], 0, s[4:5]
	v_readlane_b32 s4, v108, 1
	s_ashr_i32 s5, s4, 31
	s_lshl_b64 s[4:5], s[4:5], 10
	v_lshl_add_u64 v[4:5], v[100:101], 0, s[4:5]
	v_readlane_b32 s4, v108, 2
	s_ashr_i32 s5, s4, 31
	s_lshl_b64 s[4:5], s[4:5], 10
	v_lshl_add_u64 v[6:7], v[100:101], 0, s[4:5]
	v_readlane_b32 s4, v108, 3
	s_ashr_i32 s5, s4, 31
	v_readlane_b32 s30, v108, 5
	s_lshl_b64 s[4:5], s[4:5], 10
	s_ashr_i32 s31, s30, 31
	global_load_dwordx4 v[88:91], v[4:5], off
	global_load_dwordx4 v[80:83], v[6:7], off
	v_lshl_add_u64 v[4:5], v[100:101], 0, s[4:5]
	s_lshl_b64 s[30:31], s[30:31], 10
	global_load_dwordx4 v[68:71], v[4:5], off
	v_lshl_add_u64 v[4:5], v[100:101], 0, s[30:31]
	v_readlane_b32 s30, v108, 6
	s_ashr_i32 s31, s30, 31
	s_lshl_b64 s[30:31], s[30:31], 10
	v_lshl_add_u64 v[6:7], v[100:101], 0, s[30:31]
	v_readlane_b32 s30, v108, 7
	v_readlane_b32 s4, v108, 4
	s_ashr_i32 s31, s30, 31
	s_lshl_b64 s[30:31], s[30:31], 10
	s_ashr_i32 s5, s4, 31
	v_lshl_add_u64 v[8:9], v[100:101], 0, s[30:31]
	s_lshl_b64 s[4:5], s[4:5], 10
	v_add_co_u32_e32 v0, vcc, 0x10000, v0
	global_load_dwordx4 v[40:43], v[8:9], off
	global_load_dwordx4 v[60:63], v[4:5], off
	global_load_dwordx4 v[48:51], v[6:7], off
	v_lshl_add_u64 v[4:5], v[100:101], 0, s[4:5]
	v_addc_co_u32_e32 v1, vcc, 0, v1, vcc
	global_load_dwordx4 v[76:79], v[4:5], off
	global_load_dwordx4 v[92:95], v[2:3], off
	global_load_dword v158, v[0:1], off
	v_bfi_b32 v1, s27, v113, v112
	v_mul_f32_e32 v0, 0.5, v111
	v_add_f32_e32 v1, 1.0, v1
	v_mul_f32_e32 v0, v0, v1
	v_mul_f32_e32 v0, v110, v0
	v_mul_f32_e32 v159, v114, v0
	v_mov_b32_e32 v118, 0
	s_mov_b32 s40, 0
	v_mov_b32_e32 v119, v118
	v_mov_b32_e32 v122, v118
	v_mov_b32_e32 v123, v118
	v_mov_b32_e32 v144, v118
	v_mov_b32_e32 v145, v118
	v_mov_b32_e32 v142, v118
	v_mov_b32_e32 v143, v118
	v_mov_b32_e32 v140, v118
	v_mov_b32_e32 v141, v118
	v_mov_b32_e32 v138, v118
	v_mov_b32_e32 v139, v118
	v_mov_b32_e32 v134, v118
	v_mov_b32_e32 v135, v118
	v_mov_b32_e32 v132, v118
	v_mov_b32_e32 v133, v118
	v_mov_b32_e32 v130, v118
	v_mov_b32_e32 v131, v118
	v_mov_b32_e32 v126, v118
	v_mov_b32_e32 v127, v118
	v_mov_b32_e32 v124, v118
	v_mov_b32_e32 v125, v118
	v_mov_b32_e32 v120, v118
	v_mov_b32_e32 v121, v118
	v_mov_b32_e32 v116, v118
	v_mov_b32_e32 v117, v118
	v_mov_b32_e32 v114, v118
	v_mov_b32_e32 v115, v118
	v_mov_b32_e32 v112, v118
	v_mov_b32_e32 v113, v118
	v_mov_b32_e32 v110, v118
	v_mov_b32_e32 v111, v118
.LBB0_905:
	s_add_i32 s39, s40, 8
	v_readlane_b32 s4, v108, s39
	s_ashr_i32 s5, s4, 31
	s_lshl_b64 s[4:5], s[4:5], 10
	s_add_i32 s38, s40, 9
	v_lshl_add_u64 v[32:33], v[100:101], 0, s[4:5]
	v_readlane_b32 s4, v108, s38
	s_ashr_i32 s5, s4, 31
	s_lshl_b64 s[4:5], s[4:5], 10
	s_add_i32 s37, s40, 10
	v_lshl_add_u64 v[34:35], v[100:101], 0, s[4:5]
	v_readlane_b32 s4, v108, s37
	s_ashr_i32 s5, s4, 31
	s_lshl_b64 s[4:5], s[4:5], 10
	s_add_i32 s36, s40, 11
	global_load_dwordx4 v[84:87], v[32:33], off
	global_load_dwordx4 v[72:75], v[34:35], off
	v_lshl_add_u64 v[32:33], v[100:101], 0, s[4:5]
	v_readlane_b32 s4, v108, s36
	s_ashr_i32 s5, s4, 31
	s_lshl_b64 s[4:5], s[4:5], 10
	s_add_i32 s35, s40, 12
	v_lshl_add_u64 v[34:35], v[100:101], 0, s[4:5]
	v_readlane_b32 s4, v108, s35
	s_ashr_i32 s5, s4, 31
	s_lshl_b64 s[4:5], s[4:5], 10
	s_add_i32 s34, s40, 13
	global_load_dwordx4 v[64:67], v[32:33], off
	global_load_dwordx4 v[56:59], v[34:35], off
	v_lshl_add_u64 v[32:33], v[100:101], 0, s[4:5]
	v_readlane_b32 s4, v108, s34
	s_ashr_i32 s5, s4, 31
	s_lshl_b64 s[4:5], s[4:5], 10
	s_add_i32 s33, s40, 14
	v_lshl_add_u64 v[34:35], v[100:101], 0, s[4:5]
	v_readlane_b32 s4, v108, s33
	s_ashr_i32 s5, s4, 31
	s_lshl_b64 s[4:5], s[4:5], 10
	s_add_i32 s31, s40, 15
	global_load_dwordx4 v[52:55], v[32:33], off
	global_load_dwordx4 v[44:47], v[34:35], off
	v_lshl_add_u64 v[32:33], v[100:101], 0, s[4:5]
	v_readlane_b32 s4, v108, s31
	s_ashr_i32 s5, s4, 31
	s_lshl_b64 s[4:5], s[4:5], 10
	v_lshl_add_u64 v[34:35], v[100:101], 0, s[4:5]
	global_load_dwordx4 v[36:39], v[32:33], off
	s_nop 0
	global_load_dwordx4 v[32:35], v[34:35], off
	s_add_i32 s12, s40, 4
	s_add_i32 s30, s40, 6
	s_add_i32 s4, s40, 1
	s_add_i32 s5, s40, 2
	s_add_i32 s10, s40, 3
	s_add_i32 s14, s40, 5
	s_add_i32 s41, s40, 7
	v_readlane_b32 s16, v159, s12
	v_readlane_b32 s12, v159, s30
	s_add_i32 s30, s40, 16
	s_cmp_gt_u32 s40, 47
	v_readlane_b32 s24, v159, s40
	v_readlane_b32 s22, v159, s4
	v_readlane_b32 s20, v159, s5
	v_readlane_b32 s18, v159, s10
	v_readlane_b32 s14, v159, s14
	s_cselect_b64 s[4:5], -1, 0
	s_cmp_lt_u32 s40, 48
	v_readlane_b32 s10, v159, s41
	s_cbranch_scc0 .Lp10_dmy_907
	v_readlane_b32 s42, v108, s30
	s_ashr_i32 s43, s42, 31
	s_lshl_b64 s[42:43], s[42:43], 10
	s_add_i32 s41, s40, 17
	v_lshl_add_u64 v[0:1], v[100:101], 0, s[42:43]
	v_readlane_b32 s42, v108, s41
	s_ashr_i32 s43, s42, 31
	s_lshl_b64 s[42:43], s[42:43], 10
	s_add_i32 s41, s40, 18
	v_lshl_add_u64 v[2:3], v[100:101], 0, s[42:43]
	v_readlane_b32 s42, v108, s41
	s_ashr_i32 s43, s42, 31
	s_lshl_b64 s[42:43], s[42:43], 10
	s_add_i32 s41, s40, 19
	v_lshl_add_u64 v[8:9], v[100:101], 0, s[42:43]
	v_readlane_b32 s42, v108, s41
	s_ashr_i32 s43, s42, 31
	s_lshl_b64 s[42:43], s[42:43], 10
	s_add_i32 s41, s40, 20
	v_lshl_add_u64 v[10:11], v[100:101], 0, s[42:43]
	v_readlane_b32 s42, v108, s41
	s_ashr_i32 s43, s42, 31
	s_lshl_b64 s[42:43], s[42:43], 10
	s_add_i32 s41, s40, 21
	v_lshl_add_u64 v[16:17], v[100:101], 0, s[42:43]
	v_readlane_b32 s42, v108, s41
	s_ashr_i32 s43, s42, 31
	s_lshl_b64 s[42:43], s[42:43], 10
	s_add_i32 s41, s40, 22
	s_add_i32 s40, s40, 23
	v_lshl_add_u64 v[18:19], v[100:101], 0, s[42:43]
	v_readlane_b32 s42, v108, s41
	v_readlane_b32 s40, v108, s40
	s_ashr_i32 s43, s42, 31
	s_ashr_i32 s41, s40, 31
	s_lshl_b64 s[42:43], s[42:43], 10
	s_lshl_b64 s[40:41], s[40:41], 10
	v_lshl_add_u64 v[24:25], v[100:101], 0, s[42:43]
	v_lshl_add_u64 v[26:27], v[100:101], 0, s[40:41]
	global_load_dwordx4 v[4:7], v[0:1], off
	s_nop 0
	global_load_dwordx4 v[0:3], v[2:3], off
	s_nop 0
	global_load_dwordx4 v[12:15], v[8:9], off
	s_nop 0
	global_load_dwordx4 v[8:11], v[10:11], off
	s_nop 0
	global_load_dwordx4 v[20:23], v[16:17], off
	s_nop 0
	global_load_dwordx4 v[16:19], v[18:19], off
	s_nop 0
	global_load_dwordx4 v[28:31], v[24:25], off
	s_nop 0
	global_load_dwordx4 v[24:27], v[26:27], off
	s_branch .LBB0_907

.LBB0_907:
	s_waitcnt vmcnt(17)
	v_cvt_scalef32_pk_f32_fp4 v[160:161], v92, 1.0
	v_pk_fma_f32 v[118:119], s[24:25], v[160:161], v[118:119] op_sel_hi:[0,1,1]
	v_cvt_scalef32_pk_f32_fp4 v[160:161], v92, 1.0 op_sel:[1,0,0]
	v_pk_fma_f32 v[122:123], s[24:25], v[160:161], v[122:123] op_sel_hi:[0,1,1]
	v_cvt_scalef32_pk_f32_fp4 v[160:161], v92, 1.0 op_sel:[0,1,0]
	v_pk_fma_f32 v[144:145], s[24:25], v[160:161], v[144:145] op_sel_hi:[0,1,1]
	v_cvt_scalef32_pk_f32_fp4 v[160:161], v92, 1.0 op_sel:[1,1,0]
	v_pk_fma_f32 v[142:143], s[24:25], v[160:161], v[142:143] op_sel_hi:[0,1,1]
	v_cvt_scalef32_pk_f32_fp4 v[160:161], v93, 1.0
	v_pk_fma_f32 v[140:141], s[24:25], v[160:161], v[140:141] op_sel_hi:[0,1,1]
	v_cvt_scalef32_pk_f32_fp4 v[160:161], v93, 1.0 op_sel:[1,0,0]
	v_pk_fma_f32 v[138:139], s[24:25], v[160:161], v[138:139] op_sel_hi:[0,1,1]
	v_cvt_scalef32_pk_f32_fp4 v[160:161], v93, 1.0 op_sel:[0,1,0]
	v_cvt_scalef32_pk_f32_fp4 v[92:93], v93, 1.0 op_sel:[1,1,0]
	v_pk_fma_f32 v[92:93], s[24:25], v[92:93], v[132:133] op_sel_hi:[0,1,1]
	v_cvt_scalef32_pk_f32_fp4 v[132:133], v94, 1.0
	v_pk_fma_f32 v[130:131], s[24:25], v[132:133], v[130:131] op_sel_hi:[0,1,1]
	v_cvt_scalef32_pk_f32_fp4 v[132:133], v94, 1.0 op_sel:[1,0,0]
	v_pk_fma_f32 v[126:127], s[24:25], v[132:133], v[126:127] op_sel_hi:[0,1,1]
	v_cvt_scalef32_pk_f32_fp4 v[132:133], v94, 1.0 op_sel:[0,1,0]
	v_pk_fma_f32 v[124:125], s[24:25], v[132:133], v[124:125] op_sel_hi:[0,1,1]
	v_cvt_scalef32_pk_f32_fp4 v[132:133], v94, 1.0 op_sel:[1,1,0]
	v_pk_fma_f32 v[120:121], s[24:25], v[132:133], v[120:121] op_sel_hi:[0,1,1]
	v_cvt_scalef32_pk_f32_fp4 v[132:133], v95, 1.0
	v_pk_fma_f32 v[116:117], s[24:25], v[132:133], v[116:117] op_sel_hi:[0,1,1]
	v_cvt_scalef32_pk_f32_fp4 v[132:133], v95, 1.0 op_sel:[1,0,0]
	v_pk_fma_f32 v[114:115], s[24:25], v[132:133], v[114:115] op_sel_hi:[0,1,1]
	v_cvt_scalef32_pk_f32_fp4 v[132:133], v95, 1.0 op_sel:[0,1,0]
	v_pk_fma_f32 v[112:113], s[24:25], v[132:133], v[112:113] op_sel_hi:[0,1,1]
	v_cvt_scalef32_pk_f32_fp4 v[94:95], v95, 1.0 op_sel:[1,1,0]
	v_cvt_scalef32_pk_f32_fp4 v[132:133], v88, 1.0 op_sel:[1,1,0]
	v_pk_fma_f32 v[94:95], s[24:25], v[94:95], v[110:111] op_sel_hi:[0,1,1]
	v_cvt_scalef32_pk_f32_fp4 v[110:111], v88, 1.0
	v_pk_fma_f32 v[132:133], s[22:23], v[132:133], v[142:143] op_sel_hi:[0,1,1]
	v_cvt_scalef32_pk_f32_fp4 v[142:143], v89, 1.0
	v_pk_fma_f32 v[110:111], s[22:23], v[110:111], v[118:119] op_sel_hi:[0,1,1]
	v_cvt_scalef32_pk_f32_fp4 v[118:119], v88, 1.0 op_sel:[1,0,0]
	v_pk_fma_f32 v[140:141], s[22:23], v[142:143], v[140:141] op_sel_hi:[0,1,1]
	v_cvt_scalef32_pk_f32_fp4 v[142:143], v89, 1.0 op_sel:[1,0,0]
	v_pk_fma_f32 v[118:119], s[22:23], v[118:119], v[122:123] op_sel_hi:[0,1,1]
	v_cvt_scalef32_pk_f32_fp4 v[122:123], v88, 1.0 op_sel:[0,1,0]
	v_pk_fma_f32 v[138:139], s[22:23], v[142:143], v[138:139] op_sel_hi:[0,1,1]
	v_cvt_scalef32_pk_f32_fp4 v[142:143], v89, 1.0 op_sel:[0,1,0]
	v_cvt_scalef32_pk_f32_fp4 v[88:89], v89, 1.0 op_sel:[1,1,0]
	v_pk_fma_f32 v[88:89], s[22:23], v[88:89], v[92:93] op_sel_hi:[0,1,1]
	v_cvt_scalef32_pk_f32_fp4 v[92:93], v90, 1.0
	v_pk_fma_f32 v[92:93], s[22:23], v[92:93], v[130:131] op_sel_hi:[0,1,1]
	v_cvt_scalef32_pk_f32_fp4 v[130:131], v90, 1.0 op_sel:[1,0,0]
	v_pk_fma_f32 v[126:127], s[22:23], v[130:131], v[126:127] op_sel_hi:[0,1,1]
	v_cvt_scalef32_pk_f32_fp4 v[130:131], v90, 1.0 op_sel:[0,1,0]
	v_pk_fma_f32 v[124:125], s[22:23], v[130:131], v[124:125] op_sel_hi:[0,1,1]
	v_cvt_scalef32_pk_f32_fp4 v[130:131], v90, 1.0 op_sel:[1,1,0]
	v_pk_fma_f32 v[120:121], s[22:23], v[130:131], v[120:121] op_sel_hi:[0,1,1]
	v_cvt_scalef32_pk_f32_fp4 v[130:131], v91, 1.0
	v_pk_fma_f32 v[116:117], s[22:23], v[130:131], v[116:117] op_sel_hi:[0,1,1]
	v_cvt_scalef32_pk_f32_fp4 v[130:131], v91, 1.0 op_sel:[1,0,0]
	v_pk_fma_f32 v[114:115], s[22:23], v[130:131], v[114:115] op_sel_hi:[0,1,1]
	v_cvt_scalef32_pk_f32_fp4 v[130:131], v91, 1.0 op_sel:[0,1,0]
	v_cvt_scalef32_pk_f32_fp4 v[90:91], v91, 1.0 op_sel:[1,1,0]
	v_pk_fma_f32 v[90:91], s[22:23], v[90:91], v[94:95] op_sel_hi:[0,1,1]
	v_cvt_scalef32_pk_f32_fp4 v[94:95], v80, 1.0
	v_pk_fma_f32 v[94:95], s[20:21], v[94:95], v[110:111] op_sel_hi:[0,1,1]
	v_cvt_scalef32_pk_f32_fp4 v[110:111], v80, 1.0 op_sel:[1,0,0]
	v_pk_fma_f32 v[122:123], s[22:23], v[122:123], v[144:145] op_sel_hi:[0,1,1]
	v_pk_fma_f32 v[110:111], s[20:21], v[110:111], v[118:119] op_sel_hi:[0,1,1]
	v_cvt_scalef32_pk_f32_fp4 v[118:119], v80, 1.0 op_sel:[0,1,0]
	v_pk_fma_f32 v[118:119], s[20:21], v[118:119], v[122:123] op_sel_hi:[0,1,1]
	v_cvt_scalef32_pk_f32_fp4 v[122:123], v80, 1.0 op_sel:[1,1,0]
	v_pk_fma_f32 v[122:123], s[20:21], v[122:123], v[132:133] op_sel_hi:[0,1,1]
	v_cvt_scalef32_pk_f32_fp4 v[132:133], v81, 1.0 op_sel:[1,0,0]
	v_pk_fma_f32 v[112:113], s[22:23], v[130:131], v[112:113] op_sel_hi:[0,1,1]
	v_cvt_scalef32_pk_f32_fp4 v[130:131], v81, 1.0
	v_pk_fma_f32 v[132:133], s[20:21], v[132:133], v[138:139] op_sel_hi:[0,1,1]
	v_cvt_scalef32_pk_f32_fp4 v[138:139], v81, 1.0 op_sel:[0,1,0]
	v_cvt_scalef32_pk_f32_fp4 v[80:81], v81, 1.0 op_sel:[1,1,0]
	v_pk_fma_f32 v[80:81], s[20:21], v[80:81], v[88:89] op_sel_hi:[0,1,1]
	v_cvt_scalef32_pk_f32_fp4 v[88:89], v82, 1.0
	v_pk_fma_f32 v[88:89], s[20:21], v[88:89], v[92:93] op_sel_hi:[0,1,1]
	v_cvt_scalef32_pk_f32_fp4 v[92:93], v82, 1.0 op_sel:[1,0,0]
	v_pk_fma_f32 v[92:93], s[20:21], v[92:93], v[126:127] op_sel_hi:[0,1,1]
	v_cvt_scalef32_pk_f32_fp4 v[126:127], v82, 1.0 op_sel:[0,1,0]
	v_pk_fma_f32 v[124:125], s[20:21], v[126:127], v[124:125] op_sel_hi:[0,1,1]
	v_cvt_scalef32_pk_f32_fp4 v[126:127], v82, 1.0 op_sel:[1,1,0]
	v_pk_fma_f32 v[120:121], s[20:21], v[126:127], v[120:121] op_sel_hi:[0,1,1]
	v_cvt_scalef32_pk_f32_fp4 v[126:127], v83, 1.0
	v_pk_fma_f32 v[116:117], s[20:21], v[126:127], v[116:117] op_sel_hi:[0,1,1]
	v_cvt_scalef32_pk_f32_fp4 v[126:127], v83, 1.0 op_sel:[1,0,0]
	v_pk_fma_f32 v[114:115], s[20:21], v[126:127], v[114:115] op_sel_hi:[0,1,1]
	v_cvt_scalef32_pk_f32_fp4 v[126:127], v83, 1.0 op_sel:[0,1,0]
	v_cvt_scalef32_pk_f32_fp4 v[82:83], v83, 1.0 op_sel:[1,1,0]
	v_pk_fma_f32 v[82:83], s[20:21], v[82:83], v[90:91] op_sel_hi:[0,1,1]
	v_cvt_scalef32_pk_f32_fp4 v[90:91], v68, 1.0
	v_pk_fma_f32 v[90:91], s[18:19], v[90:91], v[94:95] op_sel_hi:[0,1,1]
	v_cvt_scalef32_pk_f32_fp4 v[94:95], v68, 1.0 op_sel:[1,0,0]
	v_pk_fma_f32 v[94:95], s[18:19], v[94:95], v[110:111] op_sel_hi:[0,1,1]
	v_cvt_scalef32_pk_f32_fp4 v[110:111], v68, 1.0 op_sel:[0,1,0]
	v_pk_fma_f32 v[110:111], s[18:19], v[110:111], v[118:119] op_sel_hi:[0,1,1]
	v_cvt_scalef32_pk_f32_fp4 v[118:119], v68, 1.0 op_sel:[1,1,0]
	v_pk_fma_f32 v[130:131], s[20:21], v[130:131], v[140:141] op_sel_hi:[0,1,1]
	v_pk_fma_f32 v[118:119], s[18:19], v[118:119], v[122:123] op_sel_hi:[0,1,1]
	v_cvt_scalef32_pk_f32_fp4 v[122:123], v69, 1.0
	v_pk_fma_f32 v[112:113], s[20:21], v[126:127], v[112:113] op_sel_hi:[0,1,1]
	v_pk_fma_f32 v[122:123], s[18:19], v[122:123], v[130:131] op_sel_hi:[0,1,1]
	v_cvt_scalef32_pk_f32_fp4 v[126:127], v69, 1.0 op_sel:[1,0,0]
	v_cvt_scalef32_pk_f32_fp4 v[130:131], v69, 1.0 op_sel:[0,1,0]
	v_cvt_scalef32_pk_f32_fp4 v[68:69], v69, 1.0 op_sel:[1,1,0]
	v_pk_fma_f32 v[68:69], s[18:19], v[68:69], v[80:81] op_sel_hi:[0,1,1]
	v_cvt_scalef32_pk_f32_fp4 v[80:81], v70, 1.0
	v_pk_fma_f32 v[80:81], s[18:19], v[80:81], v[88:89] op_sel_hi:[0,1,1]
	v_cvt_scalef32_pk_f32_fp4 v[88:89], v70, 1.0 op_sel:[1,0,0]
	v_pk_fma_f32 v[88:89], s[18:19], v[88:89], v[92:93] op_sel_hi:[0,1,1]
	v_cvt_scalef32_pk_f32_fp4 v[92:93], v70, 1.0 op_sel:[0,1,0]
	v_pk_fma_f32 v[92:93], s[18:19], v[92:93], v[124:125] op_sel_hi:[0,1,1]
	v_cvt_scalef32_pk_f32_fp4 v[124:125], v70, 1.0 op_sel:[1,1,0]
	v_pk_fma_f32 v[120:121], s[18:19], v[124:125], v[120:121] op_sel_hi:[0,1,1]
	v_cvt_scalef32_pk_f32_fp4 v[124:125], v71, 1.0
	v_pk_fma_f32 v[116:117], s[18:19], v[124:125], v[116:117] op_sel_hi:[0,1,1]
	v_cvt_scalef32_pk_f32_fp4 v[124:125], v71, 1.0 op_sel:[1,0,0]
	v_pk_fma_f32 v[114:115], s[18:19], v[124:125], v[114:115] op_sel_hi:[0,1,1]
	v_cvt_scalef32_pk_f32_fp4 v[124:125], v71, 1.0 op_sel:[0,1,0]
	v_cvt_scalef32_pk_f32_fp4 v[70:71], v71, 1.0 op_sel:[1,1,0]
	v_pk_fma_f32 v[70:71], s[18:19], v[70:71], v[82:83] op_sel_hi:[0,1,1]
	v_cvt_scalef32_pk_f32_fp4 v[82:83], v76, 1.0
	v_pk_fma_f32 v[82:83], s[16:17], v[82:83], v[90:91] op_sel_hi:[0,1,1]
	v_cvt_scalef32_pk_f32_fp4 v[90:91], v76, 1.0 op_sel:[1,0,0]
	v_pk_fma_f32 v[90:91], s[16:17], v[90:91], v[94:95] op_sel_hi:[0,1,1]
	v_cvt_scalef32_pk_f32_fp4 v[94:95], v76, 1.0 op_sel:[0,1,0]
	v_pk_fma_f32 v[94:95], s[16:17], v[94:95], v[110:111] op_sel_hi:[0,1,1]
	v_cvt_scalef32_pk_f32_fp4 v[110:111], v76, 1.0 op_sel:[1,1,0]
	v_pk_fma_f32 v[110:111], s[16:17], v[110:111], v[118:119] op_sel_hi:[0,1,1]
	v_cvt_scalef32_pk_f32_fp4 v[118:119], v77, 1.0
	v_pk_fma_f32 v[112:113], s[18:19], v[124:125], v[112:113] op_sel_hi:[0,1,1]
	v_pk_fma_f32 v[118:119], s[16:17], v[118:119], v[122:123] op_sel_hi:[0,1,1]
	v_cvt_scalef32_pk_f32_fp4 v[122:123], v77, 1.0 op_sel:[1,0,0]
	v_cvt_scalef32_pk_f32_fp4 v[124:125], v77, 1.0 op_sel:[0,1,0]
	v_cvt_scalef32_pk_f32_fp4 v[76:77], v77, 1.0 op_sel:[1,1,0]
	v_pk_fma_f32 v[68:69], s[16:17], v[76:77], v[68:69] op_sel_hi:[0,1,1]
	v_cvt_scalef32_pk_f32_fp4 v[76:77], v78, 1.0
	v_pk_fma_f32 v[76:77], s[16:17], v[76:77], v[80:81] op_sel_hi:[0,1,1]
	v_cvt_scalef32_pk_f32_fp4 v[80:81], v78, 1.0 op_sel:[1,0,0]
	v_pk_fma_f32 v[80:81], s[16:17], v[80:81], v[88:89] op_sel_hi:[0,1,1]
	v_cvt_scalef32_pk_f32_fp4 v[88:89], v78, 1.0 op_sel:[0,1,0]
	v_pk_fma_f32 v[88:89], s[16:17], v[88:89], v[92:93] op_sel_hi:[0,1,1]
	v_cvt_scalef32_pk_f32_fp4 v[92:93], v78, 1.0 op_sel:[1,1,0]
	v_pk_fma_f32 v[92:93], s[16:17], v[92:93], v[120:121] op_sel_hi:[0,1,1]
	v_cvt_scalef32_pk_f32_fp4 v[120:121], v79, 1.0
	v_pk_fma_f32 v[116:117], s[16:17], v[120:121], v[116:117] op_sel_hi:[0,1,1]
	v_cvt_scalef32_pk_f32_fp4 v[120:121], v79, 1.0 op_sel:[1,0,0]
	v_pk_fma_f32 v[114:115], s[16:17], v[120:121], v[114:115] op_sel_hi:[0,1,1]
	v_cvt_scalef32_pk_f32_fp4 v[120:121], v79, 1.0 op_sel:[0,1,0]
	v_cvt_scalef32_pk_f32_fp4 v[78:79], v79, 1.0 op_sel:[1,1,0]
	v_pk_fma_f32 v[70:71], s[16:17], v[78:79], v[70:71] op_sel_hi:[0,1,1]
	v_cvt_scalef32_pk_f32_fp4 v[78:79], v60, 1.0
	v_pk_fma_f32 v[78:79], s[14:15], v[78:79], v[82:83] op_sel_hi:[0,1,1]
	v_cvt_scalef32_pk_f32_fp4 v[82:83], v60, 1.0 op_sel:[1,0,0]
	v_pk_fma_f32 v[82:83], s[14:15], v[82:83], v[90:91] op_sel_hi:[0,1,1]
	v_cvt_scalef32_pk_f32_fp4 v[90:91], v60, 1.0 op_sel:[0,1,0]
	v_pk_fma_f32 v[90:91], s[14:15], v[90:91], v[94:95] op_sel_hi:[0,1,1]
	v_cvt_scalef32_pk_f32_fp4 v[94:95], v60, 1.0 op_sel:[1,1,0]
	v_pk_fma_f32 v[94:95], s[14:15], v[94:95], v[110:111] op_sel_hi:[0,1,1]
	v_cvt_scalef32_pk_f32_fp4 v[110:111], v61, 1.0
	v_pk_fma_f32 v[112:113], s[16:17], v[120:121], v[112:113] op_sel_hi:[0,1,1]
	v_pk_fma_f32 v[110:111], s[14:15], v[110:111], v[118:119] op_sel_hi:[0,1,1]
	v_cvt_scalef32_pk_f32_fp4 v[118:119], v61, 1.0 op_sel:[1,0,0]
	v_cvt_scalef32_pk_f32_fp4 v[120:121], v61, 1.0 op_sel:[0,1,0]
	v_cvt_scalef32_pk_f32_fp4 v[60:61], v61, 1.0 op_sel:[1,1,0]
	v_pk_fma_f32 v[60:61], s[14:15], v[60:61], v[68:69] op_sel_hi:[0,1,1]
	v_cvt_scalef32_pk_f32_fp4 v[68:69], v62, 1.0
	v_pk_fma_f32 v[68:69], s[14:15], v[68:69], v[76:77] op_sel_hi:[0,1,1]
	v_cvt_scalef32_pk_f32_fp4 v[76:77], v62, 1.0 op_sel:[1,0,0]
	v_pk_fma_f32 v[76:77], s[14:15], v[76:77], v[80:81] op_sel_hi:[0,1,1]
	v_cvt_scalef32_pk_f32_fp4 v[80:81], v62, 1.0 op_sel:[0,1,0]
	v_pk_fma_f32 v[80:81], s[14:15], v[80:81], v[88:89] op_sel_hi:[0,1,1]
	v_cvt_scalef32_pk_f32_fp4 v[88:89], v62, 1.0 op_sel:[1,1,0]
	v_pk_fma_f32 v[88:89], s[14:15], v[88:89], v[92:93] op_sel_hi:[0,1,1]
	v_cvt_scalef32_pk_f32_fp4 v[92:93], v63, 1.0
	v_pk_fma_f32 v[92:93], s[14:15], v[92:93], v[116:117] op_sel_hi:[0,1,1]
	v_cvt_scalef32_pk_f32_fp4 v[116:117], v63, 1.0 op_sel:[1,0,0]
	v_pk_fma_f32 v[114:115], s[14:15], v[116:117], v[114:115] op_sel_hi:[0,1,1]
	v_cvt_scalef32_pk_f32_fp4 v[116:117], v63, 1.0 op_sel:[0,1,0]
	v_cvt_scalef32_pk_f32_fp4 v[62:63], v63, 1.0 op_sel:[1,1,0]
	v_pk_fma_f32 v[62:63], s[14:15], v[62:63], v[70:71] op_sel_hi:[0,1,1]
	v_cvt_scalef32_pk_f32_fp4 v[70:71], v48, 1.0
	v_pk_fma_f32 v[70:71], s[12:13], v[70:71], v[78:79] op_sel_hi:[0,1,1]
	v_cvt_scalef32_pk_f32_fp4 v[78:79], v48, 1.0 op_sel:[1,0,0]
	v_pk_fma_f32 v[78:79], s[12:13], v[78:79], v[82:83] op_sel_hi:[0,1,1]
	v_cvt_scalef32_pk_f32_fp4 v[82:83], v48, 1.0 op_sel:[0,1,0]
	v_pk_fma_f32 v[82:83], s[12:13], v[82:83], v[90:91] op_sel_hi:[0,1,1]
	v_cvt_scalef32_pk_f32_fp4 v[90:91], v48, 1.0 op_sel:[1,1,0]
	v_pk_fma_f32 v[90:91], s[12:13], v[90:91], v[94:95] op_sel_hi:[0,1,1]
	v_cvt_scalef32_pk_f32_fp4 v[94:95], v49, 1.0
	v_pk_fma_f32 v[112:113], s[14:15], v[116:117], v[112:113] op_sel_hi:[0,1,1]
	v_pk_fma_f32 v[94:95], s[12:13], v[94:95], v[110:111] op_sel_hi:[0,1,1]
	v_cvt_scalef32_pk_f32_fp4 v[110:111], v49, 1.0 op_sel:[1,0,0]
	v_cvt_scalef32_pk_f32_fp4 v[116:117], v49, 1.0 op_sel:[0,1,0]
	v_cvt_scalef32_pk_f32_fp4 v[48:49], v49, 1.0 op_sel:[1,1,0]
	v_pk_fma_f32 v[48:49], s[12:13], v[48:49], v[60:61] op_sel_hi:[0,1,1]
	v_cvt_scalef32_pk_f32_fp4 v[60:61], v50, 1.0
	v_pk_fma_f32 v[60:61], s[12:13], v[60:61], v[68:69] op_sel_hi:[0,1,1]
	v_cvt_scalef32_pk_f32_fp4 v[68:69], v50, 1.0 op_sel:[1,0,0]
	v_pk_fma_f32 v[68:69], s[12:13], v[68:69], v[76:77] op_sel_hi:[0,1,1]
	v_cvt_scalef32_pk_f32_fp4 v[76:77], v50, 1.0 op_sel:[0,1,0]
	v_pk_fma_f32 v[76:77], s[12:13], v[76:77], v[80:81] op_sel_hi:[0,1,1]
	v_cvt_scalef32_pk_f32_fp4 v[80:81], v50, 1.0 op_sel:[1,1,0]
	v_pk_fma_f32 v[80:81], s[12:13], v[80:81], v[88:89] op_sel_hi:[0,1,1]
	v_cvt_scalef32_pk_f32_fp4 v[88:89], v51, 1.0
	v_pk_fma_f32 v[88:89], s[12:13], v[88:89], v[92:93] op_sel_hi:[0,1,1]
	v_cvt_scalef32_pk_f32_fp4 v[92:93], v51, 1.0 op_sel:[1,0,0]
	v_pk_fma_f32 v[92:93], s[12:13], v[92:93], v[114:115] op_sel_hi:[0,1,1]
	v_cvt_scalef32_pk_f32_fp4 v[114:115], v51, 1.0 op_sel:[0,1,0]
	v_cvt_scalef32_pk_f32_fp4 v[50:51], v51, 1.0 op_sel:[1,1,0]
	v_pk_fma_f32 v[50:51], s[12:13], v[50:51], v[62:63] op_sel_hi:[0,1,1]
	v_cvt_scalef32_pk_f32_fp4 v[62:63], v40, 1.0
	v_pk_fma_f32 v[62:63], s[10:11], v[62:63], v[70:71] op_sel_hi:[0,1,1]
	v_cvt_scalef32_pk_f32_fp4 v[70:71], v40, 1.0 op_sel:[1,0,0]
	v_pk_fma_f32 v[126:127], s[18:19], v[126:127], v[132:133] op_sel_hi:[0,1,1]
	v_pk_fma_f32 v[70:71], s[10:11], v[70:71], v[78:79] op_sel_hi:[0,1,1]
	v_cvt_scalef32_pk_f32_fp4 v[78:79], v40, 1.0 op_sel:[0,1,0]
	v_pk_fma_f32 v[122:123], s[16:17], v[122:123], v[126:127] op_sel_hi:[0,1,1]
	v_pk_fma_f32 v[78:79], s[10:11], v[78:79], v[82:83] op_sel_hi:[0,1,1]
	v_cvt_scalef32_pk_f32_fp4 v[82:83], v40, 1.0 op_sel:[1,1,0]
	v_pk_fma_f32 v[118:119], s[14:15], v[118:119], v[122:123] op_sel_hi:[0,1,1]
	v_pk_fma_f32 v[82:83], s[10:11], v[82:83], v[90:91] op_sel_hi:[0,1,1]
	v_cvt_scalef32_pk_f32_fp4 v[90:91], v41, 1.0
	v_pk_fma_f32 v[110:111], s[12:13], v[110:111], v[118:119] op_sel_hi:[0,1,1]
	v_pk_fma_f32 v[90:91], s[10:11], v[90:91], v[94:95] op_sel_hi:[0,1,1]
	v_cvt_scalef32_pk_f32_fp4 v[94:95], v41, 1.0 op_sel:[1,0,0]
	v_pk_fma_f32 v[94:95], s[10:11], v[94:95], v[110:111] op_sel_hi:[0,1,1]
	v_cvt_scalef32_pk_f32_fp4 v[110:111], v41, 1.0 op_sel:[0,1,0]
	v_cvt_scalef32_pk_f32_fp4 v[40:41], v41, 1.0 op_sel:[1,1,0]
	v_pk_fma_f32 v[134:135], s[24:25], v[160:161], v[134:135] op_sel_hi:[0,1,1]
	v_pk_fma_f32 v[40:41], s[10:11], v[40:41], v[48:49] op_sel_hi:[0,1,1]
	v_cvt_scalef32_pk_f32_fp4 v[48:49], v42, 1.0
	v_pk_fma_f32 v[134:135], s[22:23], v[142:143], v[134:135] op_sel_hi:[0,1,1]
	v_pk_fma_f32 v[48:49], s[10:11], v[48:49], v[60:61] op_sel_hi:[0,1,1]
	v_cvt_scalef32_pk_f32_fp4 v[60:61], v42, 1.0 op_sel:[1,0,0]
	v_pk_fma_f32 v[134:135], s[20:21], v[138:139], v[134:135] op_sel_hi:[0,1,1]
	v_pk_fma_f32 v[60:61], s[10:11], v[60:61], v[68:69] op_sel_hi:[0,1,1]
	v_cvt_scalef32_pk_f32_fp4 v[68:69], v42, 1.0 op_sel:[0,1,0]
	v_pk_fma_f32 v[130:131], s[18:19], v[130:131], v[134:135] op_sel_hi:[0,1,1]
	v_pk_fma_f32 v[68:69], s[10:11], v[68:69], v[76:77] op_sel_hi:[0,1,1]
	v_cvt_scalef32_pk_f32_fp4 v[76:77], v42, 1.0 op_sel:[1,1,0]
	v_pk_fma_f32 v[124:125], s[16:17], v[124:125], v[130:131] op_sel_hi:[0,1,1]
	v_pk_fma_f32 v[76:77], s[10:11], v[76:77], v[80:81] op_sel_hi:[0,1,1]
	v_cvt_scalef32_pk_f32_fp4 v[80:81], v43, 1.0
	v_pk_fma_f32 v[120:121], s[14:15], v[120:121], v[124:125] op_sel_hi:[0,1,1]
	v_pk_fma_f32 v[80:81], s[10:11], v[80:81], v[88:89] op_sel_hi:[0,1,1]
	v_cvt_scalef32_pk_f32_fp4 v[88:89], v43, 1.0 op_sel:[1,0,0]
	v_pk_fma_f32 v[116:117], s[12:13], v[116:117], v[120:121] op_sel_hi:[0,1,1]
	v_pk_fma_f32 v[112:113], s[12:13], v[114:115], v[112:113] op_sel_hi:[0,1,1]
	v_pk_fma_f32 v[88:89], s[10:11], v[88:89], v[92:93] op_sel_hi:[0,1,1]
	v_cvt_scalef32_pk_f32_fp4 v[92:93], v43, 1.0 op_sel:[0,1,0]
	v_cvt_scalef32_pk_f32_fp4 v[42:43], v43, 1.0 op_sel:[1,1,0]
	v_pk_fma_f32 v[110:111], s[10:11], v[110:111], v[116:117] op_sel_hi:[0,1,1]
	v_pk_fma_f32 v[92:93], s[10:11], v[92:93], v[112:113] op_sel_hi:[0,1,1]
	v_pk_fma_f32 v[42:43], s[10:11], v[42:43], v[50:51] op_sel_hi:[0,1,1]
	v_readlane_b32 s10, v159, s39
	s_waitcnt vmcnt(15)
	v_cvt_scalef32_pk_f32_fp4 v[50:51], v84, 1.0
	s_and_b64 vcc, exec, s[4:5]
	v_pk_fma_f32 v[50:51], s[10:11], v[50:51], v[62:63] op_sel_hi:[0,1,1]
	v_cvt_scalef32_pk_f32_fp4 v[62:63], v84, 1.0 op_sel:[1,0,0]
	v_pk_fma_f32 v[62:63], s[10:11], v[62:63], v[70:71] op_sel_hi:[0,1,1]
	v_cvt_scalef32_pk_f32_fp4 v[70:71], v84, 1.0 op_sel:[0,1,0]
	v_pk_fma_f32 v[70:71], s[10:11], v[70:71], v[78:79] op_sel_hi:[0,1,1]
	v_cvt_scalef32_pk_f32_fp4 v[78:79], v84, 1.0 op_sel:[1,1,0]
	v_pk_fma_f32 v[78:79], s[10:11], v[78:79], v[82:83] op_sel_hi:[0,1,1]
	v_cvt_scalef32_pk_f32_fp4 v[82:83], v85, 1.0
	v_pk_fma_f32 v[82:83], s[10:11], v[82:83], v[90:91] op_sel_hi:[0,1,1]
	v_cvt_scalef32_pk_f32_fp4 v[90:91], v85, 1.0 op_sel:[1,0,0]
	v_pk_fma_f32 v[90:91], s[10:11], v[90:91], v[94:95] op_sel_hi:[0,1,1]
	v_cvt_scalef32_pk_f32_fp4 v[94:95], v85, 1.0 op_sel:[0,1,0]
	v_cvt_scalef32_pk_f32_fp4 v[84:85], v85, 1.0 op_sel:[1,1,0]
	v_pk_fma_f32 v[40:41], s[10:11], v[84:85], v[40:41] op_sel_hi:[0,1,1]
	v_cvt_scalef32_pk_f32_fp4 v[84:85], v86, 1.0
	v_pk_fma_f32 v[48:49], s[10:11], v[84:85], v[48:49] op_sel_hi:[0,1,1]
	v_cvt_scalef32_pk_f32_fp4 v[84:85], v86, 1.0 op_sel:[1,0,0]
	v_pk_fma_f32 v[60:61], s[10:11], v[84:85], v[60:61] op_sel_hi:[0,1,1]
	v_cvt_scalef32_pk_f32_fp4 v[84:85], v86, 1.0 op_sel:[0,1,0]
	v_pk_fma_f32 v[68:69], s[10:11], v[84:85], v[68:69] op_sel_hi:[0,1,1]
	v_cvt_scalef32_pk_f32_fp4 v[84:85], v86, 1.0 op_sel:[1,1,0]
	v_pk_fma_f32 v[76:77], s[10:11], v[84:85], v[76:77] op_sel_hi:[0,1,1]
	v_cvt_scalef32_pk_f32_fp4 v[84:85], v87, 1.0
	v_pk_fma_f32 v[80:81], s[10:11], v[84:85], v[80:81] op_sel_hi:[0,1,1]
	v_cvt_scalef32_pk_f32_fp4 v[84:85], v87, 1.0 op_sel:[1,0,0]
	v_pk_fma_f32 v[84:85], s[10:11], v[84:85], v[88:89] op_sel_hi:[0,1,1]
	v_cvt_scalef32_pk_f32_fp4 v[88:89], v87, 1.0 op_sel:[0,1,0]
	v_cvt_scalef32_pk_f32_fp4 v[86:87], v87, 1.0 op_sel:[1,1,0]
	v_pk_fma_f32 v[94:95], s[10:11], v[94:95], v[110:111] op_sel_hi:[0,1,1]
	v_pk_fma_f32 v[88:89], s[10:11], v[88:89], v[92:93] op_sel_hi:[0,1,1]
	v_pk_fma_f32 v[42:43], s[10:11], v[86:87], v[42:43] op_sel_hi:[0,1,1]
	v_readlane_b32 s10, v159, s38
	s_waitcnt vmcnt(14)
	v_cvt_scalef32_pk_f32_fp4 v[86:87], v72, 1.0
	v_pk_fma_f32 v[50:51], s[10:11], v[86:87], v[50:51] op_sel_hi:[0,1,1]
	v_cvt_scalef32_pk_f32_fp4 v[86:87], v72, 1.0 op_sel:[1,0,0]
	v_pk_fma_f32 v[62:63], s[10:11], v[86:87], v[62:63] op_sel_hi:[0,1,1]
	v_cvt_scalef32_pk_f32_fp4 v[86:87], v72, 1.0 op_sel:[0,1,0]
	v_pk_fma_f32 v[70:71], s[10:11], v[86:87], v[70:71] op_sel_hi:[0,1,1]
	v_cvt_scalef32_pk_f32_fp4 v[86:87], v72, 1.0 op_sel:[1,1,0]
	v_pk_fma_f32 v[78:79], s[10:11], v[86:87], v[78:79] op_sel_hi:[0,1,1]
	v_cvt_scalef32_pk_f32_fp4 v[86:87], v73, 1.0
	v_pk_fma_f32 v[82:83], s[10:11], v[86:87], v[82:83] op_sel_hi:[0,1,1]
	v_cvt_scalef32_pk_f32_fp4 v[86:87], v73, 1.0 op_sel:[1,0,0]
	v_pk_fma_f32 v[86:87], s[10:11], v[86:87], v[90:91] op_sel_hi:[0,1,1]
	v_cvt_scalef32_pk_f32_fp4 v[90:91], v73, 1.0 op_sel:[0,1,0]
	v_cvt_scalef32_pk_f32_fp4 v[72:73], v73, 1.0 op_sel:[1,1,0]
	v_pk_fma_f32 v[40:41], s[10:11], v[72:73], v[40:41] op_sel_hi:[0,1,1]
	v_cvt_scalef32_pk_f32_fp4 v[72:73], v74, 1.0
	v_pk_fma_f32 v[48:49], s[10:11], v[72:73], v[48:49] op_sel_hi:[0,1,1]
	v_cvt_scalef32_pk_f32_fp4 v[72:73], v74, 1.0 op_sel:[1,0,0]
	v_pk_fma_f32 v[60:61], s[10:11], v[72:73], v[60:61] op_sel_hi:[0,1,1]
	v_cvt_scalef32_pk_f32_fp4 v[72:73], v74, 1.0 op_sel:[0,1,0]
	v_pk_fma_f32 v[68:69], s[10:11], v[72:73], v[68:69] op_sel_hi:[0,1,1]
	v_cvt_scalef32_pk_f32_fp4 v[72:73], v74, 1.0 op_sel:[1,1,0]
	v_pk_fma_f32 v[72:73], s[10:11], v[72:73], v[76:77] op_sel_hi:[0,1,1]
	v_cvt_scalef32_pk_f32_fp4 v[76:77], v75, 1.0
	v_pk_fma_f32 v[76:77], s[10:11], v[76:77], v[80:81] op_sel_hi:[0,1,1]
	v_cvt_scalef32_pk_f32_fp4 v[80:81], v75, 1.0 op_sel:[1,0,0]
	v_pk_fma_f32 v[80:81], s[10:11], v[80:81], v[84:85] op_sel_hi:[0,1,1]
	v_cvt_scalef32_pk_f32_fp4 v[84:85], v75, 1.0 op_sel:[0,1,0]
	v_cvt_scalef32_pk_f32_fp4 v[74:75], v75, 1.0 op_sel:[1,1,0]
	v_pk_fma_f32 v[90:91], s[10:11], v[90:91], v[94:95] op_sel_hi:[0,1,1]
	v_pk_fma_f32 v[84:85], s[10:11], v[84:85], v[88:89] op_sel_hi:[0,1,1]
	v_pk_fma_f32 v[42:43], s[10:11], v[74:75], v[42:43] op_sel_hi:[0,1,1]
	v_readlane_b32 s10, v159, s37
	s_waitcnt vmcnt(13)
	v_cvt_scalef32_pk_f32_fp4 v[74:75], v64, 1.0
	v_pk_fma_f32 v[50:51], s[10:11], v[74:75], v[50:51] op_sel_hi:[0,1,1]
	v_cvt_scalef32_pk_f32_fp4 v[74:75], v64, 1.0 op_sel:[1,0,0]
	v_pk_fma_f32 v[62:63], s[10:11], v[74:75], v[62:63] op_sel_hi:[0,1,1]
	v_cvt_scalef32_pk_f32_fp4 v[74:75], v64, 1.0 op_sel:[0,1,0]
	v_pk_fma_f32 v[70:71], s[10:11], v[74:75], v[70:71] op_sel_hi:[0,1,1]
	v_cvt_scalef32_pk_f32_fp4 v[74:75], v64, 1.0 op_sel:[1,1,0]
	v_pk_fma_f32 v[74:75], s[10:11], v[74:75], v[78:79] op_sel_hi:[0,1,1]
	v_cvt_scalef32_pk_f32_fp4 v[78:79], v65, 1.0
	v_pk_fma_f32 v[78:79], s[10:11], v[78:79], v[82:83] op_sel_hi:[0,1,1]
	v_cvt_scalef32_pk_f32_fp4 v[82:83], v65, 1.0 op_sel:[1,0,0]
	v_pk_fma_f32 v[82:83], s[10:11], v[82:83], v[86:87] op_sel_hi:[0,1,1]
	v_cvt_scalef32_pk_f32_fp4 v[86:87], v65, 1.0 op_sel:[0,1,0]
	v_cvt_scalef32_pk_f32_fp4 v[64:65], v65, 1.0 op_sel:[1,1,0]
	v_pk_fma_f32 v[40:41], s[10:11], v[64:65], v[40:41] op_sel_hi:[0,1,1]
	v_cvt_scalef32_pk_f32_fp4 v[64:65], v66, 1.0
	v_pk_fma_f32 v[48:49], s[10:11], v[64:65], v[48:49] op_sel_hi:[0,1,1]
	v_cvt_scalef32_pk_f32_fp4 v[64:65], v66, 1.0 op_sel:[1,0,0]
	v_pk_fma_f32 v[60:61], s[10:11], v[64:65], v[60:61] op_sel_hi:[0,1,1]
	v_cvt_scalef32_pk_f32_fp4 v[64:65], v66, 1.0 op_sel:[0,1,0]
	v_pk_fma_f32 v[64:65], s[10:11], v[64:65], v[68:69] op_sel_hi:[0,1,1]
	v_cvt_scalef32_pk_f32_fp4 v[68:69], v66, 1.0 op_sel:[1,1,0]
	v_pk_fma_f32 v[68:69], s[10:11], v[68:69], v[72:73] op_sel_hi:[0,1,1]
	v_cvt_scalef32_pk_f32_fp4 v[72:73], v67, 1.0
	v_pk_fma_f32 v[72:73], s[10:11], v[72:73], v[76:77] op_sel_hi:[0,1,1]
	v_cvt_scalef32_pk_f32_fp4 v[76:77], v67, 1.0 op_sel:[1,0,0]
	v_pk_fma_f32 v[76:77], s[10:11], v[76:77], v[80:81] op_sel_hi:[0,1,1]
	v_cvt_scalef32_pk_f32_fp4 v[80:81], v67, 1.0 op_sel:[0,1,0]
	v_cvt_scalef32_pk_f32_fp4 v[66:67], v67, 1.0 op_sel:[1,1,0]
	v_pk_fma_f32 v[86:87], s[10:11], v[86:87], v[90:91] op_sel_hi:[0,1,1]
	v_pk_fma_f32 v[80:81], s[10:11], v[80:81], v[84:85] op_sel_hi:[0,1,1]
	v_pk_fma_f32 v[42:43], s[10:11], v[66:67], v[42:43] op_sel_hi:[0,1,1]
	v_readlane_b32 s10, v159, s36
	s_waitcnt vmcnt(12)
	v_cvt_scalef32_pk_f32_fp4 v[66:67], v56, 1.0
	v_pk_fma_f32 v[50:51], s[10:11], v[66:67], v[50:51] op_sel_hi:[0,1,1]
	v_cvt_scalef32_pk_f32_fp4 v[66:67], v56, 1.0 op_sel:[1,0,0]
	v_pk_fma_f32 v[62:63], s[10:11], v[66:67], v[62:63] op_sel_hi:[0,1,1]
	v_cvt_scalef32_pk_f32_fp4 v[66:67], v56, 1.0 op_sel:[0,1,0]
	v_pk_fma_f32 v[66:67], s[10:11], v[66:67], v[70:71] op_sel_hi:[0,1,1]
	v_cvt_scalef32_pk_f32_fp4 v[70:71], v56, 1.0 op_sel:[1,1,0]
	v_pk_fma_f32 v[70:71], s[10:11], v[70:71], v[74:75] op_sel_hi:[0,1,1]
	v_cvt_scalef32_pk_f32_fp4 v[74:75], v57, 1.0
	v_pk_fma_f32 v[74:75], s[10:11], v[74:75], v[78:79] op_sel_hi:[0,1,1]
	v_cvt_scalef32_pk_f32_fp4 v[78:79], v57, 1.0 op_sel:[1,0,0]
	v_pk_fma_f32 v[78:79], s[10:11], v[78:79], v[82:83] op_sel_hi:[0,1,1]
	v_cvt_scalef32_pk_f32_fp4 v[82:83], v57, 1.0 op_sel:[0,1,0]
	v_cvt_scalef32_pk_f32_fp4 v[56:57], v57, 1.0 op_sel:[1,1,0]
	v_pk_fma_f32 v[40:41], s[10:11], v[56:57], v[40:41] op_sel_hi:[0,1,1]
	v_cvt_scalef32_pk_f32_fp4 v[56:57], v58, 1.0
	v_pk_fma_f32 v[48:49], s[10:11], v[56:57], v[48:49] op_sel_hi:[0,1,1]
	v_cvt_scalef32_pk_f32_fp4 v[56:57], v58, 1.0 op_sel:[1,0,0]
	v_pk_fma_f32 v[56:57], s[10:11], v[56:57], v[60:61] op_sel_hi:[0,1,1]
	v_cvt_scalef32_pk_f32_fp4 v[60:61], v58, 1.0 op_sel:[0,1,0]
	v_pk_fma_f32 v[60:61], s[10:11], v[60:61], v[64:65] op_sel_hi:[0,1,1]
	v_cvt_scalef32_pk_f32_fp4 v[64:65], v58, 1.0 op_sel:[1,1,0]
	v_pk_fma_f32 v[64:65], s[10:11], v[64:65], v[68:69] op_sel_hi:[0,1,1]
	v_cvt_scalef32_pk_f32_fp4 v[68:69], v59, 1.0
	v_pk_fma_f32 v[68:69], s[10:11], v[68:69], v[72:73] op_sel_hi:[0,1,1]
	v_cvt_scalef32_pk_f32_fp4 v[72:73], v59, 1.0 op_sel:[1,0,0]
	v_pk_fma_f32 v[72:73], s[10:11], v[72:73], v[76:77] op_sel_hi:[0,1,1]
	v_cvt_scalef32_pk_f32_fp4 v[76:77], v59, 1.0 op_sel:[0,1,0]
	v_cvt_scalef32_pk_f32_fp4 v[58:59], v59, 1.0 op_sel:[1,1,0]
	v_pk_fma_f32 v[82:83], s[10:11], v[82:83], v[86:87] op_sel_hi:[0,1,1]
	v_pk_fma_f32 v[76:77], s[10:11], v[76:77], v[80:81] op_sel_hi:[0,1,1]
	v_pk_fma_f32 v[42:43], s[10:11], v[58:59], v[42:43] op_sel_hi:[0,1,1]
	v_readlane_b32 s10, v159, s35
	s_waitcnt vmcnt(11)
	v_cvt_scalef32_pk_f32_fp4 v[58:59], v52, 1.0
	v_pk_fma_f32 v[50:51], s[10:11], v[58:59], v[50:51] op_sel_hi:[0,1,1]
	v_cvt_scalef32_pk_f32_fp4 v[58:59], v52, 1.0 op_sel:[1,0,0]
	v_pk_fma_f32 v[58:59], s[10:11], v[58:59], v[62:63] op_sel_hi:[0,1,1]
	v_cvt_scalef32_pk_f32_fp4 v[62:63], v52, 1.0 op_sel:[0,1,0]
	v_pk_fma_f32 v[62:63], s[10:11], v[62:63], v[66:67] op_sel_hi:[0,1,1]
	v_cvt_scalef32_pk_f32_fp4 v[66:67], v52, 1.0 op_sel:[1,1,0]
	v_pk_fma_f32 v[66:67], s[10:11], v[66:67], v[70:71] op_sel_hi:[0,1,1]
	v_cvt_scalef32_pk_f32_fp4 v[70:71], v53, 1.0
	v_pk_fma_f32 v[70:71], s[10:11], v[70:71], v[74:75] op_sel_hi:[0,1,1]
	v_cvt_scalef32_pk_f32_fp4 v[74:75], v53, 1.0 op_sel:[1,0,0]
	v_pk_fma_f32 v[74:75], s[10:11], v[74:75], v[78:79] op_sel_hi:[0,1,1]
	v_cvt_scalef32_pk_f32_fp4 v[78:79], v53, 1.0 op_sel:[0,1,0]
	v_cvt_scalef32_pk_f32_fp4 v[52:53], v53, 1.0 op_sel:[1,1,0]
	v_pk_fma_f32 v[40:41], s[10:11], v[52:53], v[40:41] op_sel_hi:[0,1,1]
	v_cvt_scalef32_pk_f32_fp4 v[52:53], v54, 1.0
	v_pk_fma_f32 v[48:49], s[10:11], v[52:53], v[48:49] op_sel_hi:[0,1,1]
	v_cvt_scalef32_pk_f32_fp4 v[52:53], v54, 1.0 op_sel:[1,0,0]
	v_pk_fma_f32 v[52:53], s[10:11], v[52:53], v[56:57] op_sel_hi:[0,1,1]
	v_cvt_scalef32_pk_f32_fp4 v[56:57], v54, 1.0 op_sel:[0,1,0]
	v_pk_fma_f32 v[56:57], s[10:11], v[56:57], v[60:61] op_sel_hi:[0,1,1]
	v_cvt_scalef32_pk_f32_fp4 v[60:61], v54, 1.0 op_sel:[1,1,0]
	v_pk_fma_f32 v[60:61], s[10:11], v[60:61], v[64:65] op_sel_hi:[0,1,1]
	v_cvt_scalef32_pk_f32_fp4 v[64:65], v55, 1.0
	v_pk_fma_f32 v[64:65], s[10:11], v[64:65], v[68:69] op_sel_hi:[0,1,1]
	v_cvt_scalef32_pk_f32_fp4 v[68:69], v55, 1.0 op_sel:[1,0,0]
	v_pk_fma_f32 v[68:69], s[10:11], v[68:69], v[72:73] op_sel_hi:[0,1,1]
	v_cvt_scalef32_pk_f32_fp4 v[72:73], v55, 1.0 op_sel:[0,1,0]
	v_cvt_scalef32_pk_f32_fp4 v[54:55], v55, 1.0 op_sel:[1,1,0]
	v_pk_fma_f32 v[78:79], s[10:11], v[78:79], v[82:83] op_sel_hi:[0,1,1]
	v_pk_fma_f32 v[72:73], s[10:11], v[72:73], v[76:77] op_sel_hi:[0,1,1]
	v_pk_fma_f32 v[42:43], s[10:11], v[54:55], v[42:43] op_sel_hi:[0,1,1]
	v_readlane_b32 s10, v159, s34
	s_waitcnt vmcnt(10)
	v_cvt_scalef32_pk_f32_fp4 v[54:55], v44, 1.0
	v_pk_fma_f32 v[50:51], s[10:11], v[54:55], v[50:51] op_sel_hi:[0,1,1]
	v_cvt_scalef32_pk_f32_fp4 v[54:55], v44, 1.0 op_sel:[1,0,0]
	v_pk_fma_f32 v[54:55], s[10:11], v[54:55], v[58:59] op_sel_hi:[0,1,1]
	v_cvt_scalef32_pk_f32_fp4 v[58:59], v44, 1.0 op_sel:[0,1,0]
	v_pk_fma_f32 v[58:59], s[10:11], v[58:59], v[62:63] op_sel_hi:[0,1,1]
	v_cvt_scalef32_pk_f32_fp4 v[62:63], v44, 1.0 op_sel:[1,1,0]
	v_pk_fma_f32 v[62:63], s[10:11], v[62:63], v[66:67] op_sel_hi:[0,1,1]
	v_cvt_scalef32_pk_f32_fp4 v[66:67], v45, 1.0
	v_pk_fma_f32 v[66:67], s[10:11], v[66:67], v[70:71] op_sel_hi:[0,1,1]
	v_cvt_scalef32_pk_f32_fp4 v[70:71], v45, 1.0 op_sel:[1,0,0]
	v_pk_fma_f32 v[70:71], s[10:11], v[70:71], v[74:75] op_sel_hi:[0,1,1]
	v_cvt_scalef32_pk_f32_fp4 v[74:75], v45, 1.0 op_sel:[0,1,0]
	v_cvt_scalef32_pk_f32_fp4 v[44:45], v45, 1.0 op_sel:[1,1,0]
	v_pk_fma_f32 v[40:41], s[10:11], v[44:45], v[40:41] op_sel_hi:[0,1,1]
	v_cvt_scalef32_pk_f32_fp4 v[44:45], v46, 1.0
	v_pk_fma_f32 v[44:45], s[10:11], v[44:45], v[48:49] op_sel_hi:[0,1,1]
	v_cvt_scalef32_pk_f32_fp4 v[48:49], v46, 1.0 op_sel:[1,0,0]
	v_pk_fma_f32 v[48:49], s[10:11], v[48:49], v[52:53] op_sel_hi:[0,1,1]
	v_cvt_scalef32_pk_f32_fp4 v[52:53], v46, 1.0 op_sel:[0,1,0]
	v_pk_fma_f32 v[52:53], s[10:11], v[52:53], v[56:57] op_sel_hi:[0,1,1]
	v_cvt_scalef32_pk_f32_fp4 v[56:57], v46, 1.0 op_sel:[1,1,0]
	v_pk_fma_f32 v[56:57], s[10:11], v[56:57], v[60:61] op_sel_hi:[0,1,1]
	v_cvt_scalef32_pk_f32_fp4 v[60:61], v47, 1.0
	v_pk_fma_f32 v[60:61], s[10:11], v[60:61], v[64:65] op_sel_hi:[0,1,1]
	v_cvt_scalef32_pk_f32_fp4 v[64:65], v47, 1.0 op_sel:[1,0,0]
	v_pk_fma_f32 v[64:65], s[10:11], v[64:65], v[68:69] op_sel_hi:[0,1,1]
	v_cvt_scalef32_pk_f32_fp4 v[68:69], v47, 1.0 op_sel:[0,1,0]
	v_cvt_scalef32_pk_f32_fp4 v[46:47], v47, 1.0 op_sel:[1,1,0]
	v_pk_fma_f32 v[74:75], s[10:11], v[74:75], v[78:79] op_sel_hi:[0,1,1]
	v_pk_fma_f32 v[68:69], s[10:11], v[68:69], v[72:73] op_sel_hi:[0,1,1]
	v_pk_fma_f32 v[42:43], s[10:11], v[46:47], v[42:43] op_sel_hi:[0,1,1]
	v_readlane_b32 s10, v159, s33
	s_waitcnt vmcnt(9)
; #define PV_LOAD(BUF, EV, S0) do { _Pragma("unroll") for (int i = 0; i < 8; ++i) { const int row_ = __builtin_amdgcn_readlane(EV, (S0) + i); BUF[i & 3][i >> 2] = *(const u32x4*)(PV8 + (size_t)row_ * 1024 + lane * 16); } } while (0)
; __global__ void __launch_bounds__(NT, 2) mk_fwd(Args args) {
;     ...
; #pragma unroll
;             for (int hh = 0; hh < 2; ++hh) {
;                 const int ev = hh ? e1 : e0; const float av = hh ? act1 : act0;
;                 PV_LOAD(bA, ev, 0);
; #pragma unroll 1
;                 for (int s = 0; s < 64; s += 16) {
;                     PV_LOAD(bB, ev, s + 8);
;                     PV_ACC(bA, av, s);
;                     if (s + 16 < 64) PV_LOAD(bA, ev, s + 16);
;                     PV_ACC(bB, av, s + 8);
	v_cvt_scalef32_pk_f32_fp4 v[46:47], v36, 1.0
	v_pk_fma_f32 v[46:47], s[10:11], v[46:47], v[50:51] op_sel_hi:[0,1,1]
	v_cvt_scalef32_pk_f32_fp4 v[50:51], v36, 1.0 op_sel:[1,0,0]
	v_pk_fma_f32 v[50:51], s[10:11], v[50:51], v[54:55] op_sel_hi:[0,1,1]
	v_cvt_scalef32_pk_f32_fp4 v[54:55], v36, 1.0 op_sel:[0,1,0]
	v_pk_fma_f32 v[54:55], s[10:11], v[54:55], v[58:59] op_sel_hi:[0,1,1]
	v_cvt_scalef32_pk_f32_fp4 v[58:59], v36, 1.0 op_sel:[1,1,0]
	v_pk_fma_f32 v[58:59], s[10:11], v[58:59], v[62:63] op_sel_hi:[0,1,1]
	v_cvt_scalef32_pk_f32_fp4 v[62:63], v37, 1.0
	v_pk_fma_f32 v[62:63], s[10:11], v[62:63], v[66:67] op_sel_hi:[0,1,1]
	v_cvt_scalef32_pk_f32_fp4 v[66:67], v37, 1.0 op_sel:[1,0,0]
	v_pk_fma_f32 v[66:67], s[10:11], v[66:67], v[70:71] op_sel_hi:[0,1,1]
	v_cvt_scalef32_pk_f32_fp4 v[70:71], v37, 1.0 op_sel:[0,1,0]
	v_cvt_scalef32_pk_f32_fp4 v[36:37], v37, 1.0 op_sel:[1,1,0]
	v_pk_fma_f32 v[36:37], s[10:11], v[36:37], v[40:41] op_sel_hi:[0,1,1]
	v_cvt_scalef32_pk_f32_fp4 v[40:41], v38, 1.0
	v_pk_fma_f32 v[40:41], s[10:11], v[40:41], v[44:45] op_sel_hi:[0,1,1]
	v_cvt_scalef32_pk_f32_fp4 v[44:45], v38, 1.0 op_sel:[1,0,0]
	v_pk_fma_f32 v[44:45], s[10:11], v[44:45], v[48:49] op_sel_hi:[0,1,1]
	v_cvt_scalef32_pk_f32_fp4 v[48:49], v38, 1.0 op_sel:[0,1,0]
	v_pk_fma_f32 v[48:49], s[10:11], v[48:49], v[52:53] op_sel_hi:[0,1,1]
	v_cvt_scalef32_pk_f32_fp4 v[52:53], v38, 1.0 op_sel:[1,1,0]
	v_pk_fma_f32 v[52:53], s[10:11], v[52:53], v[56:57] op_sel_hi:[0,1,1]
	v_cvt_scalef32_pk_f32_fp4 v[56:57], v39, 1.0
	v_pk_fma_f32 v[56:57], s[10:11], v[56:57], v[60:61] op_sel_hi:[0,1,1]
	v_cvt_scalef32_pk_f32_fp4 v[60:61], v39, 1.0 op_sel:[1,0,0]
	v_pk_fma_f32 v[60:61], s[10:11], v[60:61], v[64:65] op_sel_hi:[0,1,1]
	v_cvt_scalef32_pk_f32_fp4 v[64:65], v39, 1.0 op_sel:[0,1,0]
	v_cvt_scalef32_pk_f32_fp4 v[38:39], v39, 1.0 op_sel:[1,1,0]
	v_pk_fma_f32 v[70:71], s[10:11], v[70:71], v[74:75] op_sel_hi:[0,1,1]
	v_pk_fma_f32 v[64:65], s[10:11], v[64:65], v[68:69] op_sel_hi:[0,1,1]
	v_pk_fma_f32 v[38:39], s[10:11], v[38:39], v[42:43] op_sel_hi:[0,1,1]
	v_readlane_b32 s10, v159, s31
	s_waitcnt vmcnt(0)
	v_cvt_scalef32_pk_f32_fp4 v[42:43], v32, 1.0
	v_pk_fma_f32 v[118:119], s[10:11], v[42:43], v[46:47] op_sel_hi:[0,1,1]
	v_cvt_scalef32_pk_f32_fp4 v[42:43], v32, 1.0 op_sel:[1,0,0]
	v_pk_fma_f32 v[122:123], s[10:11], v[42:43], v[50:51] op_sel_hi:[0,1,1]
	v_cvt_scalef32_pk_f32_fp4 v[42:43], v32, 1.0 op_sel:[0,1,0]
	v_pk_fma_f32 v[144:145], s[10:11], v[42:43], v[54:55] op_sel_hi:[0,1,1]
	v_cvt_scalef32_pk_f32_fp4 v[42:43], v32, 1.0 op_sel:[1,1,0]
	v_pk_fma_f32 v[142:143], s[10:11], v[42:43], v[58:59] op_sel_hi:[0,1,1]
	v_cvt_scalef32_pk_f32_fp4 v[42:43], v33, 1.0
	v_pk_fma_f32 v[140:141], s[10:11], v[42:43], v[62:63] op_sel_hi:[0,1,1]
	v_cvt_scalef32_pk_f32_fp4 v[42:43], v33, 1.0 op_sel:[1,0,0]
	v_pk_fma_f32 v[138:139], s[10:11], v[42:43], v[66:67] op_sel_hi:[0,1,1]
	v_cvt_scalef32_pk_f32_fp4 v[42:43], v33, 1.0 op_sel:[0,1,0]
	v_cvt_scalef32_pk_f32_fp4 v[32:33], v33, 1.0 op_sel:[1,1,0]
	v_pk_fma_f32 v[132:133], s[10:11], v[32:33], v[36:37] op_sel_hi:[0,1,1]
	v_cvt_scalef32_pk_f32_fp4 v[32:33], v34, 1.0
	v_pk_fma_f32 v[130:131], s[10:11], v[32:33], v[40:41] op_sel_hi:[0,1,1]
	v_cvt_scalef32_pk_f32_fp4 v[32:33], v34, 1.0 op_sel:[1,0,0]
	v_pk_fma_f32 v[126:127], s[10:11], v[32:33], v[44:45] op_sel_hi:[0,1,1]
	v_cvt_scalef32_pk_f32_fp4 v[32:33], v34, 1.0 op_sel:[0,1,0]
	v_pk_fma_f32 v[124:125], s[10:11], v[32:33], v[48:49] op_sel_hi:[0,1,1]
	v_cvt_scalef32_pk_f32_fp4 v[32:33], v34, 1.0 op_sel:[1,1,0]
	v_pk_fma_f32 v[120:121], s[10:11], v[32:33], v[52:53] op_sel_hi:[0,1,1]
	v_cvt_scalef32_pk_f32_fp4 v[32:33], v35, 1.0
	v_pk_fma_f32 v[116:117], s[10:11], v[32:33], v[56:57] op_sel_hi:[0,1,1]
	v_cvt_scalef32_pk_f32_fp4 v[32:33], v35, 1.0 op_sel:[1,0,0]
	v_pk_fma_f32 v[114:115], s[10:11], v[32:33], v[60:61] op_sel_hi:[0,1,1]
	v_cvt_scalef32_pk_f32_fp4 v[32:33], v35, 1.0 op_sel:[0,1,0]
	v_pk_fma_f32 v[112:113], s[10:11], v[32:33], v[64:65] op_sel_hi:[0,1,1]
	v_cvt_scalef32_pk_f32_fp4 v[32:33], v35, 1.0 op_sel:[1,1,0]
	v_pk_fma_f32 v[134:135], s[10:11], v[42:43], v[70:71] op_sel_hi:[0,1,1]
	v_pk_fma_f32 v[110:111], s[10:11], v[32:33], v[38:39] op_sel_hi:[0,1,1]
	s_cbranch_vccnz .LBB0_909
	v_mov_b64_e32 v[42:43], v[26:27]
	v_mov_b64_e32 v[70:71], v[10:11]
	v_mov_b64_e32 v[50:51], v[30:31]
	v_mov_b64_e32 v[82:83], v[14:15]
	v_mov_b64_e32 v[62:63], v[18:19]
	v_mov_b64_e32 v[90:91], v[2:3]
	v_mov_b64_e32 v[78:79], v[22:23]
	v_mov_b64_e32 v[94:95], v[6:7]
	v_mov_b64_e32 v[40:41], v[24:25]
	v_mov_b64_e32 v[68:69], v[8:9]
	v_mov_b64_e32 v[48:49], v[28:29]
	v_mov_b64_e32 v[80:81], v[12:13]
	v_mov_b64_e32 v[60:61], v[16:17]
	v_mov_b64_e32 v[88:89], v[0:1]
	v_mov_b64_e32 v[76:77], v[20:21]
	v_mov_b64_e32 v[92:93], v[4:5]
	s_mov_b32 s40, s30
	s_branch .LBB0_905
.LBB0_909:
	v_readlane_b32 s30, v106, 1
	s_ashr_i32 s31, s30, 31
	s_lshl_b64 s[30:31], s[30:31], 10
	v_lshl_add_u64 v[0:1], v[100:101], 0, s[30:31]
	v_readlane_b32 s30, v106, 2
	s_ashr_i32 s31, s30, 31
	s_lshl_b64 s[30:31], s[30:31], 10
	v_lshl_add_u64 v[2:3], v[100:101], 0, s[30:31]
	v_readlane_b32 s30, v106, 3
	s_ashr_i32 s31, s30, 31
	s_lshl_b64 s[30:31], s[30:31], 10
	v_lshl_add_u64 v[4:5], v[100:101], 0, s[30:31]
	v_readlane_b32 s30, v106, 4
	v_readlane_b32 s34, v106, 6
	s_ashr_i32 s31, s30, 31
	s_ashr_i32 s35, s34, 31
	s_lshl_b64 s[30:31], s[30:31], 10
	s_lshl_b64 s[34:35], s[34:35], 10
	v_readlane_b32 s4, v106, 0
	global_load_dwordx4 v[80:83], v[2:3], off
	global_load_dwordx4 v[68:71], v[4:5], off
	v_lshl_add_u64 v[2:3], v[100:101], 0, s[30:31]
	v_readlane_b32 s30, v106, 5
	v_lshl_add_u64 v[4:5], v[100:101], 0, s[34:35]
	v_readlane_b32 s34, v106, 7
	s_ashr_i32 s5, s4, 31
	s_ashr_i32 s31, s30, 31
	s_ashr_i32 s35, s34, 31
	s_lshl_b64 s[4:5], s[4:5], 10
	s_lshl_b64 s[34:35], s[34:35], 10
	s_lshl_b64 s[30:31], s[30:31], 10
	v_lshl_add_u64 v[6:7], v[100:101], 0, s[34:35]
	global_load_dwordx4 v[48:51], v[4:5], off
	global_load_dwordx4 v[40:43], v[6:7], off
	v_lshl_add_u64 v[4:5], v[100:101], 0, s[30:31]
	global_load_dwordx4 v[76:79], v[2:3], off
	global_load_dwordx4 v[60:63], v[4:5], off
	global_load_dwordx4 v[88:91], v[0:1], off
	v_lshl_add_u64 v[0:1], v[100:101], 0, s[4:5]
	global_load_dwordx4 v[92:95], v[0:1], off
	v_bfi_b32 v1, s27, v157, v109
	v_mul_f32_e32 v0, 0.5, v107
	v_add_f32_e32 v1, 1.0, v1
	v_mul_f32_e32 v0, v0, v1
	v_mul_f32_e32 v0, v156, v0
	v_mul_f32_e32 v107, v158, v0
	s_mov_b32 s40, 0
	s_branch .LBB0_911
; #define PV_LOAD(BUF, EV, S0) do { _Pragma("unroll") for (int i = 0; i < 8; ++i) { const int row_ = __builtin_amdgcn_readlane(EV, (S0) + i); BUF[i & 3][i >> 2] = *(const u32x4*)(PV8 + (size_t)row_ * 1024 + lane * 16); } } while (0)
; __global__ void __launch_bounds__(NT, 2) mk_fwd(Args args) {
;     ...
; #pragma unroll
;             for (int hh = 0; hh < 2; ++hh) {
;                 const int ev = hh ? e1 : e0; const float av = hh ? act1 : act0;
;                 PV_LOAD(bA, ev, 0);
; #pragma unroll 1
;                 for (int s = 0; s < 64; s += 16) {
;                     PV_LOAD(bB, ev, s + 8);
;                     PV_ACC(bA, av, s);
;                     if (s + 16 < 64) PV_LOAD(bA, ev, s + 16);
;                     PV_ACC(bB, av, s + 8);
.LBB0_910:
	s_waitcnt vmcnt(16)
	v_cvt_scalef32_pk_f32_fp4 v[108:109], v92, 1.0
	v_pk_fma_f32 v[108:109], s[24:25], v[108:109], v[118:119] op_sel_hi:[0,1,1]
	v_cvt_scalef32_pk_f32_fp4 v[118:119], v92, 1.0 op_sel:[1,0,0]
	v_pk_fma_f32 v[118:119], s[24:25], v[118:119], v[122:123] op_sel_hi:[0,1,1]
	v_cvt_scalef32_pk_f32_fp4 v[122:123], v92, 1.0 op_sel:[0,1,0]
	v_pk_fma_f32 v[122:123], s[24:25], v[122:123], v[144:145] op_sel_hi:[0,1,1]
	v_cvt_scalef32_pk_f32_fp4 v[144:145], v92, 1.0 op_sel:[1,1,0]
	v_pk_fma_f32 v[142:143], s[24:25], v[144:145], v[142:143] op_sel_hi:[0,1,1]
	v_cvt_scalef32_pk_f32_fp4 v[144:145], v93, 1.0
	v_pk_fma_f32 v[140:141], s[24:25], v[144:145], v[140:141] op_sel_hi:[0,1,1]
	v_cvt_scalef32_pk_f32_fp4 v[144:145], v93, 1.0 op_sel:[1,0,0]
	v_pk_fma_f32 v[138:139], s[24:25], v[144:145], v[138:139] op_sel_hi:[0,1,1]
	v_cvt_scalef32_pk_f32_fp4 v[144:145], v93, 1.0 op_sel:[0,1,0]
	v_cvt_scalef32_pk_f32_fp4 v[92:93], v93, 1.0 op_sel:[1,1,0]
	v_pk_fma_f32 v[92:93], s[24:25], v[92:93], v[132:133] op_sel_hi:[0,1,1]
	v_cvt_scalef32_pk_f32_fp4 v[132:133], v94, 1.0
	v_pk_fma_f32 v[130:131], s[24:25], v[132:133], v[130:131] op_sel_hi:[0,1,1]
	v_cvt_scalef32_pk_f32_fp4 v[132:133], v94, 1.0 op_sel:[1,0,0]
	v_pk_fma_f32 v[126:127], s[24:25], v[132:133], v[126:127] op_sel_hi:[0,1,1]
	v_cvt_scalef32_pk_f32_fp4 v[132:133], v94, 1.0 op_sel:[0,1,0]
	v_pk_fma_f32 v[124:125], s[24:25], v[132:133], v[124:125] op_sel_hi:[0,1,1]
	v_cvt_scalef32_pk_f32_fp4 v[132:133], v94, 1.0 op_sel:[1,1,0]
	v_pk_fma_f32 v[120:121], s[24:25], v[132:133], v[120:121] op_sel_hi:[0,1,1]
	v_cvt_scalef32_pk_f32_fp4 v[132:133], v95, 1.0
	v_pk_fma_f32 v[116:117], s[24:25], v[132:133], v[116:117] op_sel_hi:[0,1,1]
	v_cvt_scalef32_pk_f32_fp4 v[132:133], v95, 1.0 op_sel:[1,0,0]
	v_pk_fma_f32 v[114:115], s[24:25], v[132:133], v[114:115] op_sel_hi:[0,1,1]
	v_cvt_scalef32_pk_f32_fp4 v[132:133], v95, 1.0 op_sel:[0,1,0]
	v_cvt_scalef32_pk_f32_fp4 v[94:95], v95, 1.0 op_sel:[1,1,0]
	v_pk_fma_f32 v[94:95], s[24:25], v[94:95], v[110:111] op_sel_hi:[0,1,1]
	v_cvt_scalef32_pk_f32_fp4 v[110:111], v88, 1.0
	v_pk_fma_f32 v[112:113], s[24:25], v[132:133], v[112:113] op_sel_hi:[0,1,1]
	v_pk_fma_f32 v[108:109], s[22:23], v[110:111], v[108:109] op_sel_hi:[0,1,1]
	v_cvt_scalef32_pk_f32_fp4 v[110:111], v88, 1.0 op_sel:[1,0,0]
	v_cvt_scalef32_pk_f32_fp4 v[132:133], v89, 1.0
	v_pk_fma_f32 v[110:111], s[22:23], v[110:111], v[118:119] op_sel_hi:[0,1,1]
	v_cvt_scalef32_pk_f32_fp4 v[118:119], v88, 1.0 op_sel:[0,1,0]
	v_pk_fma_f32 v[132:133], s[22:23], v[132:133], v[140:141] op_sel_hi:[0,1,1]
	v_cvt_scalef32_pk_f32_fp4 v[140:141], v89, 1.0 op_sel:[1,0,0]
	v_pk_fma_f32 v[118:119], s[22:23], v[118:119], v[122:123] op_sel_hi:[0,1,1]
	v_cvt_scalef32_pk_f32_fp4 v[122:123], v88, 1.0 op_sel:[1,1,0]
	v_pk_fma_f32 v[138:139], s[22:23], v[140:141], v[138:139] op_sel_hi:[0,1,1]
	v_cvt_scalef32_pk_f32_fp4 v[140:141], v89, 1.0 op_sel:[0,1,0]
	v_cvt_scalef32_pk_f32_fp4 v[88:89], v89, 1.0 op_sel:[1,1,0]
	v_pk_fma_f32 v[88:89], s[22:23], v[88:89], v[92:93] op_sel_hi:[0,1,1]
	v_cvt_scalef32_pk_f32_fp4 v[92:93], v90, 1.0
	v_pk_fma_f32 v[92:93], s[22:23], v[92:93], v[130:131] op_sel_hi:[0,1,1]
	v_cvt_scalef32_pk_f32_fp4 v[130:131], v90, 1.0 op_sel:[1,0,0]
	v_pk_fma_f32 v[126:127], s[22:23], v[130:131], v[126:127] op_sel_hi:[0,1,1]
	v_cvt_scalef32_pk_f32_fp4 v[130:131], v90, 1.0 op_sel:[0,1,0]
	v_pk_fma_f32 v[124:125], s[22:23], v[130:131], v[124:125] op_sel_hi:[0,1,1]
	v_cvt_scalef32_pk_f32_fp4 v[130:131], v90, 1.0 op_sel:[1,1,0]
	v_pk_fma_f32 v[120:121], s[22:23], v[130:131], v[120:121] op_sel_hi:[0,1,1]
	v_cvt_scalef32_pk_f32_fp4 v[130:131], v91, 1.0
	v_pk_fma_f32 v[116:117], s[22:23], v[130:131], v[116:117] op_sel_hi:[0,1,1]
	v_cvt_scalef32_pk_f32_fp4 v[130:131], v91, 1.0 op_sel:[1,0,0]
	v_pk_fma_f32 v[114:115], s[22:23], v[130:131], v[114:115] op_sel_hi:[0,1,1]
	v_cvt_scalef32_pk_f32_fp4 v[130:131], v91, 1.0 op_sel:[0,1,0]
	v_cvt_scalef32_pk_f32_fp4 v[90:91], v91, 1.0 op_sel:[1,1,0]
	v_pk_fma_f32 v[90:91], s[22:23], v[90:91], v[94:95] op_sel_hi:[0,1,1]
	v_cvt_scalef32_pk_f32_fp4 v[94:95], v80, 1.0
	v_pk_fma_f32 v[94:95], s[20:21], v[94:95], v[108:109] op_sel_hi:[0,1,1]
	v_cvt_scalef32_pk_f32_fp4 v[108:109], v80, 1.0 op_sel:[1,0,0]
	v_pk_fma_f32 v[108:109], s[20:21], v[108:109], v[110:111] op_sel_hi:[0,1,1]
	v_cvt_scalef32_pk_f32_fp4 v[110:111], v80, 1.0 op_sel:[0,1,0]
	v_pk_fma_f32 v[122:123], s[22:23], v[122:123], v[142:143] op_sel_hi:[0,1,1]
	v_pk_fma_f32 v[110:111], s[20:21], v[110:111], v[118:119] op_sel_hi:[0,1,1]
	v_cvt_scalef32_pk_f32_fp4 v[118:119], v80, 1.0 op_sel:[1,1,0]
	v_pk_fma_f32 v[118:119], s[20:21], v[118:119], v[122:123] op_sel_hi:[0,1,1]
	v_cvt_scalef32_pk_f32_fp4 v[122:123], v81, 1.0
	v_pk_fma_f32 v[112:113], s[22:23], v[130:131], v[112:113] op_sel_hi:[0,1,1]
	v_pk_fma_f32 v[122:123], s[20:21], v[122:123], v[132:133] op_sel_hi:[0,1,1]
	v_cvt_scalef32_pk_f32_fp4 v[130:131], v81, 1.0 op_sel:[1,0,0]
	v_cvt_scalef32_pk_f32_fp4 v[132:133], v81, 1.0 op_sel:[0,1,0]
	v_cvt_scalef32_pk_f32_fp4 v[80:81], v81, 1.0 op_sel:[1,1,0]
	v_pk_fma_f32 v[80:81], s[20:21], v[80:81], v[88:89] op_sel_hi:[0,1,1]
	v_cvt_scalef32_pk_f32_fp4 v[88:89], v82, 1.0
	v_pk_fma_f32 v[88:89], s[20:21], v[88:89], v[92:93] op_sel_hi:[0,1,1]
	v_cvt_scalef32_pk_f32_fp4 v[92:93], v82, 1.0 op_sel:[1,0,0]
	v_pk_fma_f32 v[92:93], s[20:21], v[92:93], v[126:127] op_sel_hi:[0,1,1]
	v_cvt_scalef32_pk_f32_fp4 v[126:127], v82, 1.0 op_sel:[0,1,0]
	v_pk_fma_f32 v[124:125], s[20:21], v[126:127], v[124:125] op_sel_hi:[0,1,1]
	v_cvt_scalef32_pk_f32_fp4 v[126:127], v82, 1.0 op_sel:[1,1,0]
	v_pk_fma_f32 v[120:121], s[20:21], v[126:127], v[120:121] op_sel_hi:[0,1,1]
	v_cvt_scalef32_pk_f32_fp4 v[126:127], v83, 1.0
	v_pk_fma_f32 v[116:117], s[20:21], v[126:127], v[116:117] op_sel_hi:[0,1,1]
	v_cvt_scalef32_pk_f32_fp4 v[126:127], v83, 1.0 op_sel:[1,0,0]
	v_pk_fma_f32 v[114:115], s[20:21], v[126:127], v[114:115] op_sel_hi:[0,1,1]
	v_cvt_scalef32_pk_f32_fp4 v[126:127], v83, 1.0 op_sel:[0,1,0]
	v_cvt_scalef32_pk_f32_fp4 v[82:83], v83, 1.0 op_sel:[1,1,0]
	v_pk_fma_f32 v[82:83], s[20:21], v[82:83], v[90:91] op_sel_hi:[0,1,1]
	v_cvt_scalef32_pk_f32_fp4 v[90:91], v68, 1.0
	v_pk_fma_f32 v[90:91], s[18:19], v[90:91], v[94:95] op_sel_hi:[0,1,1]
	v_cvt_scalef32_pk_f32_fp4 v[94:95], v68, 1.0 op_sel:[1,0,0]
	v_pk_fma_f32 v[94:95], s[18:19], v[94:95], v[108:109] op_sel_hi:[0,1,1]
	v_cvt_scalef32_pk_f32_fp4 v[108:109], v68, 1.0 op_sel:[0,1,0]
	v_pk_fma_f32 v[108:109], s[18:19], v[108:109], v[110:111] op_sel_hi:[0,1,1]
	v_cvt_scalef32_pk_f32_fp4 v[110:111], v68, 1.0 op_sel:[1,1,0]
	v_pk_fma_f32 v[110:111], s[18:19], v[110:111], v[118:119] op_sel_hi:[0,1,1]
	v_cvt_scalef32_pk_f32_fp4 v[118:119], v69, 1.0
	v_pk_fma_f32 v[112:113], s[20:21], v[126:127], v[112:113] op_sel_hi:[0,1,1]
	v_pk_fma_f32 v[118:119], s[18:19], v[118:119], v[122:123] op_sel_hi:[0,1,1]
	v_cvt_scalef32_pk_f32_fp4 v[122:123], v69, 1.0 op_sel:[1,0,0]
	v_cvt_scalef32_pk_f32_fp4 v[126:127], v69, 1.0 op_sel:[0,1,0]
	v_cvt_scalef32_pk_f32_fp4 v[68:69], v69, 1.0 op_sel:[1,1,0]
	v_pk_fma_f32 v[68:69], s[18:19], v[68:69], v[80:81] op_sel_hi:[0,1,1]
	v_cvt_scalef32_pk_f32_fp4 v[80:81], v70, 1.0
	v_pk_fma_f32 v[80:81], s[18:19], v[80:81], v[88:89] op_sel_hi:[0,1,1]
	v_cvt_scalef32_pk_f32_fp4 v[88:89], v70, 1.0 op_sel:[1,0,0]
	v_pk_fma_f32 v[88:89], s[18:19], v[88:89], v[92:93] op_sel_hi:[0,1,1]
	v_cvt_scalef32_pk_f32_fp4 v[92:93], v70, 1.0 op_sel:[0,1,0]
	v_pk_fma_f32 v[92:93], s[18:19], v[92:93], v[124:125] op_sel_hi:[0,1,1]
	v_cvt_scalef32_pk_f32_fp4 v[124:125], v70, 1.0 op_sel:[1,1,0]
	v_pk_fma_f32 v[120:121], s[18:19], v[124:125], v[120:121] op_sel_hi:[0,1,1]
	v_cvt_scalef32_pk_f32_fp4 v[124:125], v71, 1.0
	v_pk_fma_f32 v[116:117], s[18:19], v[124:125], v[116:117] op_sel_hi:[0,1,1]
	v_cvt_scalef32_pk_f32_fp4 v[124:125], v71, 1.0 op_sel:[1,0,0]
	v_pk_fma_f32 v[114:115], s[18:19], v[124:125], v[114:115] op_sel_hi:[0,1,1]
	v_cvt_scalef32_pk_f32_fp4 v[124:125], v71, 1.0 op_sel:[0,1,0]
	v_cvt_scalef32_pk_f32_fp4 v[70:71], v71, 1.0 op_sel:[1,1,0]
	v_pk_fma_f32 v[70:71], s[18:19], v[70:71], v[82:83] op_sel_hi:[0,1,1]
	v_cvt_scalef32_pk_f32_fp4 v[82:83], v76, 1.0
	v_pk_fma_f32 v[82:83], s[16:17], v[82:83], v[90:91] op_sel_hi:[0,1,1]
	v_cvt_scalef32_pk_f32_fp4 v[90:91], v76, 1.0 op_sel:[1,0,0]
	v_pk_fma_f32 v[90:91], s[16:17], v[90:91], v[94:95] op_sel_hi:[0,1,1]
	v_cvt_scalef32_pk_f32_fp4 v[94:95], v76, 1.0 op_sel:[0,1,0]
	v_pk_fma_f32 v[94:95], s[16:17], v[94:95], v[108:109] op_sel_hi:[0,1,1]
	v_cvt_scalef32_pk_f32_fp4 v[108:109], v76, 1.0 op_sel:[1,1,0]
	v_pk_fma_f32 v[130:131], s[20:21], v[130:131], v[138:139] op_sel_hi:[0,1,1]
	v_pk_fma_f32 v[108:109], s[16:17], v[108:109], v[110:111] op_sel_hi:[0,1,1]
	v_cvt_scalef32_pk_f32_fp4 v[110:111], v77, 1.0
	v_pk_fma_f32 v[122:123], s[18:19], v[122:123], v[130:131] op_sel_hi:[0,1,1]
	v_pk_fma_f32 v[110:111], s[16:17], v[110:111], v[118:119] op_sel_hi:[0,1,1]
	v_cvt_scalef32_pk_f32_fp4 v[118:119], v77, 1.0 op_sel:[1,0,0]
	v_pk_fma_f32 v[118:119], s[16:17], v[118:119], v[122:123] op_sel_hi:[0,1,1]
	v_cvt_scalef32_pk_f32_fp4 v[122:123], v77, 1.0 op_sel:[0,1,0]
	v_cvt_scalef32_pk_f32_fp4 v[76:77], v77, 1.0 op_sel:[1,1,0]
	v_pk_fma_f32 v[68:69], s[16:17], v[76:77], v[68:69] op_sel_hi:[0,1,1]
	v_cvt_scalef32_pk_f32_fp4 v[76:77], v78, 1.0
	v_pk_fma_f32 v[76:77], s[16:17], v[76:77], v[80:81] op_sel_hi:[0,1,1]
	v_cvt_scalef32_pk_f32_fp4 v[80:81], v78, 1.0 op_sel:[1,0,0]
	v_pk_fma_f32 v[80:81], s[16:17], v[80:81], v[88:89] op_sel_hi:[0,1,1]
	v_cvt_scalef32_pk_f32_fp4 v[88:89], v78, 1.0 op_sel:[0,1,0]
	v_pk_fma_f32 v[88:89], s[16:17], v[88:89], v[92:93] op_sel_hi:[0,1,1]
	v_cvt_scalef32_pk_f32_fp4 v[92:93], v78, 1.0 op_sel:[1,1,0]
	v_pk_fma_f32 v[92:93], s[16:17], v[92:93], v[120:121] op_sel_hi:[0,1,1]
	v_cvt_scalef32_pk_f32_fp4 v[120:121], v79, 1.0
	v_pk_fma_f32 v[116:117], s[16:17], v[120:121], v[116:117] op_sel_hi:[0,1,1]
	v_cvt_scalef32_pk_f32_fp4 v[120:121], v79, 1.0 op_sel:[1,0,0]
	v_pk_fma_f32 v[114:115], s[16:17], v[120:121], v[114:115] op_sel_hi:[0,1,1]
	v_cvt_scalef32_pk_f32_fp4 v[120:121], v79, 1.0 op_sel:[0,1,0]
	v_cvt_scalef32_pk_f32_fp4 v[78:79], v79, 1.0 op_sel:[1,1,0]
	v_pk_fma_f32 v[70:71], s[16:17], v[78:79], v[70:71] op_sel_hi:[0,1,1]
	v_cvt_scalef32_pk_f32_fp4 v[78:79], v60, 1.0
	v_pk_fma_f32 v[78:79], s[14:15], v[78:79], v[82:83] op_sel_hi:[0,1,1]
	v_cvt_scalef32_pk_f32_fp4 v[82:83], v60, 1.0 op_sel:[1,0,0]
	v_pk_fma_f32 v[82:83], s[14:15], v[82:83], v[90:91] op_sel_hi:[0,1,1]
	v_cvt_scalef32_pk_f32_fp4 v[90:91], v60, 1.0 op_sel:[0,1,0]
	v_pk_fma_f32 v[90:91], s[14:15], v[90:91], v[94:95] op_sel_hi:[0,1,1]
	v_cvt_scalef32_pk_f32_fp4 v[94:95], v60, 1.0 op_sel:[1,1,0]
	v_pk_fma_f32 v[94:95], s[14:15], v[94:95], v[108:109] op_sel_hi:[0,1,1]
	v_cvt_scalef32_pk_f32_fp4 v[108:109], v61, 1.0
	v_pk_fma_f32 v[108:109], s[14:15], v[108:109], v[110:111] op_sel_hi:[0,1,1]
	v_cvt_scalef32_pk_f32_fp4 v[110:111], v61, 1.0 op_sel:[1,0,0]
	v_pk_fma_f32 v[110:111], s[14:15], v[110:111], v[118:119] op_sel_hi:[0,1,1]
	v_cvt_scalef32_pk_f32_fp4 v[118:119], v61, 1.0 op_sel:[0,1,0]
	v_cvt_scalef32_pk_f32_fp4 v[60:61], v61, 1.0 op_sel:[1,1,0]
	v_pk_fma_f32 v[60:61], s[14:15], v[60:61], v[68:69] op_sel_hi:[0,1,1]
	v_cvt_scalef32_pk_f32_fp4 v[68:69], v62, 1.0
	v_pk_fma_f32 v[68:69], s[14:15], v[68:69], v[76:77] op_sel_hi:[0,1,1]
	v_cvt_scalef32_pk_f32_fp4 v[76:77], v62, 1.0 op_sel:[1,0,0]
	v_pk_fma_f32 v[76:77], s[14:15], v[76:77], v[80:81] op_sel_hi:[0,1,1]
	v_cvt_scalef32_pk_f32_fp4 v[80:81], v62, 1.0 op_sel:[0,1,0]
	v_pk_fma_f32 v[80:81], s[14:15], v[80:81], v[88:89] op_sel_hi:[0,1,1]
	v_cvt_scalef32_pk_f32_fp4 v[88:89], v62, 1.0 op_sel:[1,1,0]
	v_pk_fma_f32 v[88:89], s[14:15], v[88:89], v[92:93] op_sel_hi:[0,1,1]
	v_cvt_scalef32_pk_f32_fp4 v[92:93], v63, 1.0
	v_pk_fma_f32 v[92:93], s[14:15], v[92:93], v[116:117] op_sel_hi:[0,1,1]
	v_cvt_scalef32_pk_f32_fp4 v[116:117], v63, 1.0 op_sel:[1,0,0]
	v_pk_fma_f32 v[114:115], s[14:15], v[116:117], v[114:115] op_sel_hi:[0,1,1]
	v_cvt_scalef32_pk_f32_fp4 v[116:117], v63, 1.0 op_sel:[0,1,0]
	v_cvt_scalef32_pk_f32_fp4 v[62:63], v63, 1.0 op_sel:[1,1,0]
	v_pk_fma_f32 v[62:63], s[14:15], v[62:63], v[70:71] op_sel_hi:[0,1,1]
	v_cvt_scalef32_pk_f32_fp4 v[70:71], v48, 1.0
	v_pk_fma_f32 v[70:71], s[12:13], v[70:71], v[78:79] op_sel_hi:[0,1,1]
	v_cvt_scalef32_pk_f32_fp4 v[78:79], v48, 1.0 op_sel:[1,0,0]
	v_pk_fma_f32 v[78:79], s[12:13], v[78:79], v[82:83] op_sel_hi:[0,1,1]
	v_cvt_scalef32_pk_f32_fp4 v[82:83], v48, 1.0 op_sel:[0,1,0]
	v_pk_fma_f32 v[82:83], s[12:13], v[82:83], v[90:91] op_sel_hi:[0,1,1]
	v_cvt_scalef32_pk_f32_fp4 v[90:91], v48, 1.0 op_sel:[1,1,0]
	v_pk_fma_f32 v[90:91], s[12:13], v[90:91], v[94:95] op_sel_hi:[0,1,1]
	v_cvt_scalef32_pk_f32_fp4 v[94:95], v49, 1.0
	v_pk_fma_f32 v[94:95], s[12:13], v[94:95], v[108:109] op_sel_hi:[0,1,1]
	v_cvt_scalef32_pk_f32_fp4 v[108:109], v49, 1.0 op_sel:[1,0,0]
	v_pk_fma_f32 v[108:109], s[12:13], v[108:109], v[110:111] op_sel_hi:[0,1,1]
	v_cvt_scalef32_pk_f32_fp4 v[110:111], v49, 1.0 op_sel:[0,1,0]
	v_cvt_scalef32_pk_f32_fp4 v[48:49], v49, 1.0 op_sel:[1,1,0]
	v_pk_fma_f32 v[48:49], s[12:13], v[48:49], v[60:61] op_sel_hi:[0,1,1]
	v_cvt_scalef32_pk_f32_fp4 v[60:61], v50, 1.0
	v_pk_fma_f32 v[60:61], s[12:13], v[60:61], v[68:69] op_sel_hi:[0,1,1]
	v_cvt_scalef32_pk_f32_fp4 v[68:69], v50, 1.0 op_sel:[1,0,0]
	v_pk_fma_f32 v[68:69], s[12:13], v[68:69], v[76:77] op_sel_hi:[0,1,1]
	v_cvt_scalef32_pk_f32_fp4 v[76:77], v50, 1.0 op_sel:[0,1,0]
	v_pk_fma_f32 v[76:77], s[12:13], v[76:77], v[80:81] op_sel_hi:[0,1,1]
	v_cvt_scalef32_pk_f32_fp4 v[80:81], v50, 1.0 op_sel:[1,1,0]
	v_pk_fma_f32 v[80:81], s[12:13], v[80:81], v[88:89] op_sel_hi:[0,1,1]
	v_cvt_scalef32_pk_f32_fp4 v[88:89], v51, 1.0
	v_pk_fma_f32 v[88:89], s[12:13], v[88:89], v[92:93] op_sel_hi:[0,1,1]
	v_cvt_scalef32_pk_f32_fp4 v[92:93], v51, 1.0 op_sel:[1,0,0]
	v_pk_fma_f32 v[92:93], s[12:13], v[92:93], v[114:115] op_sel_hi:[0,1,1]
	v_cvt_scalef32_pk_f32_fp4 v[114:115], v51, 1.0 op_sel:[0,1,0]
	v_cvt_scalef32_pk_f32_fp4 v[50:51], v51, 1.0 op_sel:[1,1,0]
	v_pk_fma_f32 v[50:51], s[12:13], v[50:51], v[62:63] op_sel_hi:[0,1,1]
	v_cvt_scalef32_pk_f32_fp4 v[62:63], v40, 1.0
	v_pk_fma_f32 v[62:63], s[10:11], v[62:63], v[70:71] op_sel_hi:[0,1,1]
	v_cvt_scalef32_pk_f32_fp4 v[70:71], v40, 1.0 op_sel:[1,0,0]
	v_pk_fma_f32 v[70:71], s[10:11], v[70:71], v[78:79] op_sel_hi:[0,1,1]
	v_cvt_scalef32_pk_f32_fp4 v[78:79], v40, 1.0 op_sel:[0,1,0]
	v_pk_fma_f32 v[78:79], s[10:11], v[78:79], v[82:83] op_sel_hi:[0,1,1]
	v_cvt_scalef32_pk_f32_fp4 v[82:83], v40, 1.0 op_sel:[1,1,0]
	v_pk_fma_f32 v[82:83], s[10:11], v[82:83], v[90:91] op_sel_hi:[0,1,1]
	v_cvt_scalef32_pk_f32_fp4 v[90:91], v41, 1.0
	v_pk_fma_f32 v[90:91], s[10:11], v[90:91], v[94:95] op_sel_hi:[0,1,1]
	v_cvt_scalef32_pk_f32_fp4 v[94:95], v41, 1.0 op_sel:[1,0,0]
	v_pk_fma_f32 v[94:95], s[10:11], v[94:95], v[108:109] op_sel_hi:[0,1,1]
	v_cvt_scalef32_pk_f32_fp4 v[108:109], v41, 1.0 op_sel:[0,1,0]
	v_cvt_scalef32_pk_f32_fp4 v[40:41], v41, 1.0 op_sel:[1,1,0]
	v_pk_fma_f32 v[134:135], s[24:25], v[144:145], v[134:135] op_sel_hi:[0,1,1]
	v_pk_fma_f32 v[40:41], s[10:11], v[40:41], v[48:49] op_sel_hi:[0,1,1]
	v_cvt_scalef32_pk_f32_fp4 v[48:49], v42, 1.0
	v_pk_fma_f32 v[134:135], s[22:23], v[140:141], v[134:135] op_sel_hi:[0,1,1]
	v_pk_fma_f32 v[48:49], s[10:11], v[48:49], v[60:61] op_sel_hi:[0,1,1]
	v_cvt_scalef32_pk_f32_fp4 v[60:61], v42, 1.0 op_sel:[1,0,0]
	v_pk_fma_f32 v[132:133], s[20:21], v[132:133], v[134:135] op_sel_hi:[0,1,1]
	v_pk_fma_f32 v[60:61], s[10:11], v[60:61], v[68:69] op_sel_hi:[0,1,1]
	v_cvt_scalef32_pk_f32_fp4 v[68:69], v42, 1.0 op_sel:[0,1,0]
	v_pk_fma_f32 v[126:127], s[18:19], v[126:127], v[132:133] op_sel_hi:[0,1,1]
	v_pk_fma_f32 v[112:113], s[18:19], v[124:125], v[112:113] op_sel_hi:[0,1,1]
	v_pk_fma_f32 v[68:69], s[10:11], v[68:69], v[76:77] op_sel_hi:[0,1,1]
	v_cvt_scalef32_pk_f32_fp4 v[76:77], v42, 1.0 op_sel:[1,1,0]
	v_pk_fma_f32 v[122:123], s[16:17], v[122:123], v[126:127] op_sel_hi:[0,1,1]
	v_pk_fma_f32 v[112:113], s[16:17], v[120:121], v[112:113] op_sel_hi:[0,1,1]
	v_pk_fma_f32 v[76:77], s[10:11], v[76:77], v[80:81] op_sel_hi:[0,1,1]
	v_cvt_scalef32_pk_f32_fp4 v[80:81], v43, 1.0
	v_pk_fma_f32 v[118:119], s[14:15], v[118:119], v[122:123] op_sel_hi:[0,1,1]
	v_pk_fma_f32 v[112:113], s[14:15], v[116:117], v[112:113] op_sel_hi:[0,1,1]
	v_pk_fma_f32 v[80:81], s[10:11], v[80:81], v[88:89] op_sel_hi:[0,1,1]
	v_cvt_scalef32_pk_f32_fp4 v[88:89], v43, 1.0 op_sel:[1,0,0]
	v_pk_fma_f32 v[110:111], s[12:13], v[110:111], v[118:119] op_sel_hi:[0,1,1]
	v_pk_fma_f32 v[112:113], s[12:13], v[114:115], v[112:113] op_sel_hi:[0,1,1]
	v_pk_fma_f32 v[88:89], s[10:11], v[88:89], v[92:93] op_sel_hi:[0,1,1]
	v_cvt_scalef32_pk_f32_fp4 v[92:93], v43, 1.0 op_sel:[0,1,0]
	v_cvt_scalef32_pk_f32_fp4 v[42:43], v43, 1.0 op_sel:[1,1,0]
	v_pk_fma_f32 v[108:109], s[10:11], v[108:109], v[110:111] op_sel_hi:[0,1,1]
	v_pk_fma_f32 v[92:93], s[10:11], v[92:93], v[112:113] op_sel_hi:[0,1,1]
	v_pk_fma_f32 v[42:43], s[10:11], v[42:43], v[50:51] op_sel_hi:[0,1,1]
	v_readlane_b32 s10, v107, s39
	s_waitcnt vmcnt(15)
	v_cvt_scalef32_pk_f32_fp4 v[50:51], v84, 1.0
	s_andn2_b64 vcc, exec, s[4:5]
	v_pk_fma_f32 v[50:51], s[10:11], v[50:51], v[62:63] op_sel_hi:[0,1,1]
	v_cvt_scalef32_pk_f32_fp4 v[62:63], v84, 1.0 op_sel:[1,0,0]
	v_pk_fma_f32 v[62:63], s[10:11], v[62:63], v[70:71] op_sel_hi:[0,1,1]
	v_cvt_scalef32_pk_f32_fp4 v[70:71], v84, 1.0 op_sel:[0,1,0]
	v_pk_fma_f32 v[70:71], s[10:11], v[70:71], v[78:79] op_sel_hi:[0,1,1]
	v_cvt_scalef32_pk_f32_fp4 v[78:79], v84, 1.0 op_sel:[1,1,0]
	v_pk_fma_f32 v[78:79], s[10:11], v[78:79], v[82:83] op_sel_hi:[0,1,1]
	v_cvt_scalef32_pk_f32_fp4 v[82:83], v85, 1.0
	v_pk_fma_f32 v[82:83], s[10:11], v[82:83], v[90:91] op_sel_hi:[0,1,1]
	v_cvt_scalef32_pk_f32_fp4 v[90:91], v85, 1.0 op_sel:[1,0,0]
	v_pk_fma_f32 v[90:91], s[10:11], v[90:91], v[94:95] op_sel_hi:[0,1,1]
	v_cvt_scalef32_pk_f32_fp4 v[94:95], v85, 1.0 op_sel:[0,1,0]
	v_cvt_scalef32_pk_f32_fp4 v[84:85], v85, 1.0 op_sel:[1,1,0]
	v_pk_fma_f32 v[40:41], s[10:11], v[84:85], v[40:41] op_sel_hi:[0,1,1]
	v_cvt_scalef32_pk_f32_fp4 v[84:85], v86, 1.0
	v_pk_fma_f32 v[48:49], s[10:11], v[84:85], v[48:49] op_sel_hi:[0,1,1]
	v_cvt_scalef32_pk_f32_fp4 v[84:85], v86, 1.0 op_sel:[1,0,0]
	v_pk_fma_f32 v[60:61], s[10:11], v[84:85], v[60:61] op_sel_hi:[0,1,1]
	v_cvt_scalef32_pk_f32_fp4 v[84:85], v86, 1.0 op_sel:[0,1,0]
	v_pk_fma_f32 v[68:69], s[10:11], v[84:85], v[68:69] op_sel_hi:[0,1,1]
	v_cvt_scalef32_pk_f32_fp4 v[84:85], v86, 1.0 op_sel:[1,1,0]
	v_pk_fma_f32 v[76:77], s[10:11], v[84:85], v[76:77] op_sel_hi:[0,1,1]
	v_cvt_scalef32_pk_f32_fp4 v[84:85], v87, 1.0
	v_pk_fma_f32 v[80:81], s[10:11], v[84:85], v[80:81] op_sel_hi:[0,1,1]
	v_cvt_scalef32_pk_f32_fp4 v[84:85], v87, 1.0 op_sel:[1,0,0]
	v_pk_fma_f32 v[84:85], s[10:11], v[84:85], v[88:89] op_sel_hi:[0,1,1]
	v_cvt_scalef32_pk_f32_fp4 v[88:89], v87, 1.0 op_sel:[0,1,0]
	v_cvt_scalef32_pk_f32_fp4 v[86:87], v87, 1.0 op_sel:[1,1,0]
	v_pk_fma_f32 v[94:95], s[10:11], v[94:95], v[108:109] op_sel_hi:[0,1,1]
	v_pk_fma_f32 v[88:89], s[10:11], v[88:89], v[92:93] op_sel_hi:[0,1,1]
	v_pk_fma_f32 v[42:43], s[10:11], v[86:87], v[42:43] op_sel_hi:[0,1,1]
	v_readlane_b32 s10, v107, s38
	s_waitcnt vmcnt(14)
	v_cvt_scalef32_pk_f32_fp4 v[86:87], v72, 1.0
	s_mov_b32 s40, s30
	v_pk_fma_f32 v[50:51], s[10:11], v[86:87], v[50:51] op_sel_hi:[0,1,1]
	v_cvt_scalef32_pk_f32_fp4 v[86:87], v72, 1.0 op_sel:[1,0,0]
	v_pk_fma_f32 v[62:63], s[10:11], v[86:87], v[62:63] op_sel_hi:[0,1,1]
	v_cvt_scalef32_pk_f32_fp4 v[86:87], v72, 1.0 op_sel:[0,1,0]
	v_pk_fma_f32 v[70:71], s[10:11], v[86:87], v[70:71] op_sel_hi:[0,1,1]
	v_cvt_scalef32_pk_f32_fp4 v[86:87], v72, 1.0 op_sel:[1,1,0]
	v_pk_fma_f32 v[78:79], s[10:11], v[86:87], v[78:79] op_sel_hi:[0,1,1]
	v_cvt_scalef32_pk_f32_fp4 v[86:87], v73, 1.0
	v_pk_fma_f32 v[82:83], s[10:11], v[86:87], v[82:83] op_sel_hi:[0,1,1]
	v_cvt_scalef32_pk_f32_fp4 v[86:87], v73, 1.0 op_sel:[1,0,0]
	v_pk_fma_f32 v[86:87], s[10:11], v[86:87], v[90:91] op_sel_hi:[0,1,1]
	v_cvt_scalef32_pk_f32_fp4 v[90:91], v73, 1.0 op_sel:[0,1,0]
	v_cvt_scalef32_pk_f32_fp4 v[72:73], v73, 1.0 op_sel:[1,1,0]
	v_pk_fma_f32 v[40:41], s[10:11], v[72:73], v[40:41] op_sel_hi:[0,1,1]
	v_cvt_scalef32_pk_f32_fp4 v[72:73], v74, 1.0
	v_pk_fma_f32 v[48:49], s[10:11], v[72:73], v[48:49] op_sel_hi:[0,1,1]
	v_cvt_scalef32_pk_f32_fp4 v[72:73], v74, 1.0 op_sel:[1,0,0]
	v_pk_fma_f32 v[60:61], s[10:11], v[72:73], v[60:61] op_sel_hi:[0,1,1]
	v_cvt_scalef32_pk_f32_fp4 v[72:73], v74, 1.0 op_sel:[0,1,0]
	v_pk_fma_f32 v[68:69], s[10:11], v[72:73], v[68:69] op_sel_hi:[0,1,1]
	v_cvt_scalef32_pk_f32_fp4 v[72:73], v74, 1.0 op_sel:[1,1,0]
	v_pk_fma_f32 v[72:73], s[10:11], v[72:73], v[76:77] op_sel_hi:[0,1,1]
	v_cvt_scalef32_pk_f32_fp4 v[76:77], v75, 1.0
	v_pk_fma_f32 v[76:77], s[10:11], v[76:77], v[80:81] op_sel_hi:[0,1,1]
	v_cvt_scalef32_pk_f32_fp4 v[80:81], v75, 1.0 op_sel:[1,0,0]
	v_pk_fma_f32 v[80:81], s[10:11], v[80:81], v[84:85] op_sel_hi:[0,1,1]
	v_cvt_scalef32_pk_f32_fp4 v[84:85], v75, 1.0 op_sel:[0,1,0]
	v_cvt_scalef32_pk_f32_fp4 v[74:75], v75, 1.0 op_sel:[1,1,0]
	v_pk_fma_f32 v[90:91], s[10:11], v[90:91], v[94:95] op_sel_hi:[0,1,1]
	v_pk_fma_f32 v[84:85], s[10:11], v[84:85], v[88:89] op_sel_hi:[0,1,1]
	v_pk_fma_f32 v[42:43], s[10:11], v[74:75], v[42:43] op_sel_hi:[0,1,1]
	v_readlane_b32 s10, v107, s37
	s_waitcnt vmcnt(13)
	v_cvt_scalef32_pk_f32_fp4 v[74:75], v64, 1.0
	v_pk_fma_f32 v[50:51], s[10:11], v[74:75], v[50:51] op_sel_hi:[0,1,1]
	v_cvt_scalef32_pk_f32_fp4 v[74:75], v64, 1.0 op_sel:[1,0,0]
	v_pk_fma_f32 v[62:63], s[10:11], v[74:75], v[62:63] op_sel_hi:[0,1,1]
	v_cvt_scalef32_pk_f32_fp4 v[74:75], v64, 1.0 op_sel:[0,1,0]
	v_pk_fma_f32 v[70:71], s[10:11], v[74:75], v[70:71] op_sel_hi:[0,1,1]
	v_cvt_scalef32_pk_f32_fp4 v[74:75], v64, 1.0 op_sel:[1,1,0]
	v_pk_fma_f32 v[74:75], s[10:11], v[74:75], v[78:79] op_sel_hi:[0,1,1]
	v_cvt_scalef32_pk_f32_fp4 v[78:79], v65, 1.0
	v_pk_fma_f32 v[78:79], s[10:11], v[78:79], v[82:83] op_sel_hi:[0,1,1]
	v_cvt_scalef32_pk_f32_fp4 v[82:83], v65, 1.0 op_sel:[1,0,0]
	v_pk_fma_f32 v[82:83], s[10:11], v[82:83], v[86:87] op_sel_hi:[0,1,1]
	v_cvt_scalef32_pk_f32_fp4 v[86:87], v65, 1.0 op_sel:[0,1,0]
	v_cvt_scalef32_pk_f32_fp4 v[64:65], v65, 1.0 op_sel:[1,1,0]
	v_pk_fma_f32 v[40:41], s[10:11], v[64:65], v[40:41] op_sel_hi:[0,1,1]
	v_cvt_scalef32_pk_f32_fp4 v[64:65], v66, 1.0
	v_pk_fma_f32 v[48:49], s[10:11], v[64:65], v[48:49] op_sel_hi:[0,1,1]
	v_cvt_scalef32_pk_f32_fp4 v[64:65], v66, 1.0 op_sel:[1,0,0]
	v_pk_fma_f32 v[60:61], s[10:11], v[64:65], v[60:61] op_sel_hi:[0,1,1]
	v_cvt_scalef32_pk_f32_fp4 v[64:65], v66, 1.0 op_sel:[0,1,0]
	v_pk_fma_f32 v[64:65], s[10:11], v[64:65], v[68:69] op_sel_hi:[0,1,1]
	v_cvt_scalef32_pk_f32_fp4 v[68:69], v66, 1.0 op_sel:[1,1,0]
	v_pk_fma_f32 v[68:69], s[10:11], v[68:69], v[72:73] op_sel_hi:[0,1,1]
	v_cvt_scalef32_pk_f32_fp4 v[72:73], v67, 1.0
	v_pk_fma_f32 v[72:73], s[10:11], v[72:73], v[76:77] op_sel_hi:[0,1,1]
	v_cvt_scalef32_pk_f32_fp4 v[76:77], v67, 1.0 op_sel:[1,0,0]
	v_pk_fma_f32 v[76:77], s[10:11], v[76:77], v[80:81] op_sel_hi:[0,1,1]
	v_cvt_scalef32_pk_f32_fp4 v[80:81], v67, 1.0 op_sel:[0,1,0]
	v_cvt_scalef32_pk_f32_fp4 v[66:67], v67, 1.0 op_sel:[1,1,0]
	v_pk_fma_f32 v[86:87], s[10:11], v[86:87], v[90:91] op_sel_hi:[0,1,1]
	v_pk_fma_f32 v[80:81], s[10:11], v[80:81], v[84:85] op_sel_hi:[0,1,1]
	v_pk_fma_f32 v[42:43], s[10:11], v[66:67], v[42:43] op_sel_hi:[0,1,1]
	v_readlane_b32 s10, v107, s36
	s_waitcnt vmcnt(12)
	v_cvt_scalef32_pk_f32_fp4 v[66:67], v56, 1.0
	v_pk_fma_f32 v[50:51], s[10:11], v[66:67], v[50:51] op_sel_hi:[0,1,1]
	v_cvt_scalef32_pk_f32_fp4 v[66:67], v56, 1.0 op_sel:[1,0,0]
	v_pk_fma_f32 v[62:63], s[10:11], v[66:67], v[62:63] op_sel_hi:[0,1,1]
	v_cvt_scalef32_pk_f32_fp4 v[66:67], v56, 1.0 op_sel:[0,1,0]
	v_pk_fma_f32 v[66:67], s[10:11], v[66:67], v[70:71] op_sel_hi:[0,1,1]
	v_cvt_scalef32_pk_f32_fp4 v[70:71], v56, 1.0 op_sel:[1,1,0]
	v_pk_fma_f32 v[70:71], s[10:11], v[70:71], v[74:75] op_sel_hi:[0,1,1]
	v_cvt_scalef32_pk_f32_fp4 v[74:75], v57, 1.0
	v_pk_fma_f32 v[74:75], s[10:11], v[74:75], v[78:79] op_sel_hi:[0,1,1]
	v_cvt_scalef32_pk_f32_fp4 v[78:79], v57, 1.0 op_sel:[1,0,0]
	v_pk_fma_f32 v[78:79], s[10:11], v[78:79], v[82:83] op_sel_hi:[0,1,1]
	v_cvt_scalef32_pk_f32_fp4 v[82:83], v57, 1.0 op_sel:[0,1,0]
	v_cvt_scalef32_pk_f32_fp4 v[56:57], v57, 1.0 op_sel:[1,1,0]
	v_pk_fma_f32 v[40:41], s[10:11], v[56:57], v[40:41] op_sel_hi:[0,1,1]
	v_cvt_scalef32_pk_f32_fp4 v[56:57], v58, 1.0
	v_pk_fma_f32 v[48:49], s[10:11], v[56:57], v[48:49] op_sel_hi:[0,1,1]
	v_cvt_scalef32_pk_f32_fp4 v[56:57], v58, 1.0 op_sel:[1,0,0]
	v_pk_fma_f32 v[56:57], s[10:11], v[56:57], v[60:61] op_sel_hi:[0,1,1]
	v_cvt_scalef32_pk_f32_fp4 v[60:61], v58, 1.0 op_sel:[0,1,0]
	v_pk_fma_f32 v[60:61], s[10:11], v[60:61], v[64:65] op_sel_hi:[0,1,1]
	v_cvt_scalef32_pk_f32_fp4 v[64:65], v58, 1.0 op_sel:[1,1,0]
	v_pk_fma_f32 v[64:65], s[10:11], v[64:65], v[68:69] op_sel_hi:[0,1,1]
	v_cvt_scalef32_pk_f32_fp4 v[68:69], v59, 1.0
	v_pk_fma_f32 v[68:69], s[10:11], v[68:69], v[72:73] op_sel_hi:[0,1,1]
	v_cvt_scalef32_pk_f32_fp4 v[72:73], v59, 1.0 op_sel:[1,0,0]
	v_pk_fma_f32 v[72:73], s[10:11], v[72:73], v[76:77] op_sel_hi:[0,1,1]
	v_cvt_scalef32_pk_f32_fp4 v[76:77], v59, 1.0 op_sel:[0,1,0]
	v_cvt_scalef32_pk_f32_fp4 v[58:59], v59, 1.0 op_sel:[1,1,0]
	v_pk_fma_f32 v[82:83], s[10:11], v[82:83], v[86:87] op_sel_hi:[0,1,1]
	v_pk_fma_f32 v[76:77], s[10:11], v[76:77], v[80:81] op_sel_hi:[0,1,1]
	v_pk_fma_f32 v[42:43], s[10:11], v[58:59], v[42:43] op_sel_hi:[0,1,1]
	v_readlane_b32 s10, v107, s35
	s_waitcnt vmcnt(11)
	v_cvt_scalef32_pk_f32_fp4 v[58:59], v52, 1.0
	v_pk_fma_f32 v[50:51], s[10:11], v[58:59], v[50:51] op_sel_hi:[0,1,1]
	v_cvt_scalef32_pk_f32_fp4 v[58:59], v52, 1.0 op_sel:[1,0,0]
	v_pk_fma_f32 v[58:59], s[10:11], v[58:59], v[62:63] op_sel_hi:[0,1,1]
	v_cvt_scalef32_pk_f32_fp4 v[62:63], v52, 1.0 op_sel:[0,1,0]
	v_pk_fma_f32 v[62:63], s[10:11], v[62:63], v[66:67] op_sel_hi:[0,1,1]
	v_cvt_scalef32_pk_f32_fp4 v[66:67], v52, 1.0 op_sel:[1,1,0]
	v_pk_fma_f32 v[66:67], s[10:11], v[66:67], v[70:71] op_sel_hi:[0,1,1]
	v_cvt_scalef32_pk_f32_fp4 v[70:71], v53, 1.0
	v_pk_fma_f32 v[70:71], s[10:11], v[70:71], v[74:75] op_sel_hi:[0,1,1]
	v_cvt_scalef32_pk_f32_fp4 v[74:75], v53, 1.0 op_sel:[1,0,0]
	v_pk_fma_f32 v[74:75], s[10:11], v[74:75], v[78:79] op_sel_hi:[0,1,1]
	v_cvt_scalef32_pk_f32_fp4 v[78:79], v53, 1.0 op_sel:[0,1,0]
	v_cvt_scalef32_pk_f32_fp4 v[52:53], v53, 1.0 op_sel:[1,1,0]
	v_pk_fma_f32 v[40:41], s[10:11], v[52:53], v[40:41] op_sel_hi:[0,1,1]
	v_cvt_scalef32_pk_f32_fp4 v[52:53], v54, 1.0
	v_pk_fma_f32 v[48:49], s[10:11], v[52:53], v[48:49] op_sel_hi:[0,1,1]
	v_cvt_scalef32_pk_f32_fp4 v[52:53], v54, 1.0 op_sel:[1,0,0]
	v_pk_fma_f32 v[52:53], s[10:11], v[52:53], v[56:57] op_sel_hi:[0,1,1]
	v_cvt_scalef32_pk_f32_fp4 v[56:57], v54, 1.0 op_sel:[0,1,0]
	v_pk_fma_f32 v[56:57], s[10:11], v[56:57], v[60:61] op_sel_hi:[0,1,1]
	v_cvt_scalef32_pk_f32_fp4 v[60:61], v54, 1.0 op_sel:[1,1,0]
	v_pk_fma_f32 v[60:61], s[10:11], v[60:61], v[64:65] op_sel_hi:[0,1,1]
	v_cvt_scalef32_pk_f32_fp4 v[64:65], v55, 1.0
	v_pk_fma_f32 v[64:65], s[10:11], v[64:65], v[68:69] op_sel_hi:[0,1,1]
	v_cvt_scalef32_pk_f32_fp4 v[68:69], v55, 1.0 op_sel:[1,0,0]
	v_pk_fma_f32 v[68:69], s[10:11], v[68:69], v[72:73] op_sel_hi:[0,1,1]
	v_cvt_scalef32_pk_f32_fp4 v[72:73], v55, 1.0 op_sel:[0,1,0]
	v_cvt_scalef32_pk_f32_fp4 v[54:55], v55, 1.0 op_sel:[1,1,0]
	v_pk_fma_f32 v[78:79], s[10:11], v[78:79], v[82:83] op_sel_hi:[0,1,1]
	v_pk_fma_f32 v[72:73], s[10:11], v[72:73], v[76:77] op_sel_hi:[0,1,1]
	v_pk_fma_f32 v[42:43], s[10:11], v[54:55], v[42:43] op_sel_hi:[0,1,1]
	v_readlane_b32 s10, v107, s34
	s_waitcnt vmcnt(10)
	v_cvt_scalef32_pk_f32_fp4 v[54:55], v44, 1.0
	v_pk_fma_f32 v[50:51], s[10:11], v[54:55], v[50:51] op_sel_hi:[0,1,1]
	v_cvt_scalef32_pk_f32_fp4 v[54:55], v44, 1.0 op_sel:[1,0,0]
	v_pk_fma_f32 v[54:55], s[10:11], v[54:55], v[58:59] op_sel_hi:[0,1,1]
	v_cvt_scalef32_pk_f32_fp4 v[58:59], v44, 1.0 op_sel:[0,1,0]
	v_pk_fma_f32 v[58:59], s[10:11], v[58:59], v[62:63] op_sel_hi:[0,1,1]
	v_cvt_scalef32_pk_f32_fp4 v[62:63], v44, 1.0 op_sel:[1,1,0]
	v_pk_fma_f32 v[62:63], s[10:11], v[62:63], v[66:67] op_sel_hi:[0,1,1]
	v_cvt_scalef32_pk_f32_fp4 v[66:67], v45, 1.0
	v_pk_fma_f32 v[66:67], s[10:11], v[66:67], v[70:71] op_sel_hi:[0,1,1]
	v_cvt_scalef32_pk_f32_fp4 v[70:71], v45, 1.0 op_sel:[1,0,0]
	v_pk_fma_f32 v[70:71], s[10:11], v[70:71], v[74:75] op_sel_hi:[0,1,1]
	v_cvt_scalef32_pk_f32_fp4 v[74:75], v45, 1.0 op_sel:[0,1,0]
	v_cvt_scalef32_pk_f32_fp4 v[44:45], v45, 1.0 op_sel:[1,1,0]
	v_pk_fma_f32 v[40:41], s[10:11], v[44:45], v[40:41] op_sel_hi:[0,1,1]
	v_cvt_scalef32_pk_f32_fp4 v[44:45], v46, 1.0
	v_pk_fma_f32 v[44:45], s[10:11], v[44:45], v[48:49] op_sel_hi:[0,1,1]
	v_cvt_scalef32_pk_f32_fp4 v[48:49], v46, 1.0 op_sel:[1,0,0]
	v_pk_fma_f32 v[48:49], s[10:11], v[48:49], v[52:53] op_sel_hi:[0,1,1]
	v_cvt_scalef32_pk_f32_fp4 v[52:53], v46, 1.0 op_sel:[0,1,0]
	v_pk_fma_f32 v[52:53], s[10:11], v[52:53], v[56:57] op_sel_hi:[0,1,1]
	v_cvt_scalef32_pk_f32_fp4 v[56:57], v46, 1.0 op_sel:[1,1,0]
	v_pk_fma_f32 v[56:57], s[10:11], v[56:57], v[60:61] op_sel_hi:[0,1,1]
	v_cvt_scalef32_pk_f32_fp4 v[60:61], v47, 1.0
	v_pk_fma_f32 v[60:61], s[10:11], v[60:61], v[64:65] op_sel_hi:[0,1,1]
	v_cvt_scalef32_pk_f32_fp4 v[64:65], v47, 1.0 op_sel:[1,0,0]
	v_pk_fma_f32 v[64:65], s[10:11], v[64:65], v[68:69] op_sel_hi:[0,1,1]
	v_cvt_scalef32_pk_f32_fp4 v[68:69], v47, 1.0 op_sel:[0,1,0]
	v_cvt_scalef32_pk_f32_fp4 v[46:47], v47, 1.0 op_sel:[1,1,0]
	v_pk_fma_f32 v[74:75], s[10:11], v[74:75], v[78:79] op_sel_hi:[0,1,1]
	v_pk_fma_f32 v[68:69], s[10:11], v[68:69], v[72:73] op_sel_hi:[0,1,1]
	v_pk_fma_f32 v[42:43], s[10:11], v[46:47], v[42:43] op_sel_hi:[0,1,1]
	v_readlane_b32 s10, v107, s33
	s_waitcnt vmcnt(9)
; #define PV_LOAD(BUF, EV, S0) do { _Pragma("unroll") for (int i = 0; i < 8; ++i) { const int row_ = __builtin_amdgcn_readlane(EV, (S0) + i); BUF[i & 3][i >> 2] = *(const u32x4*)(PV8 + (size_t)row_ * 1024 + lane * 16); } } while (0)
; __global__ void __launch_bounds__(NT, 2) mk_fwd(Args args) {
;     ...
; #pragma unroll
;             for (int hh = 0; hh < 2; ++hh) {
;                 const int ev = hh ? e1 : e0; const float av = hh ? act1 : act0;
;                 PV_LOAD(bA, ev, 0);
; #pragma unroll 1
;                 for (int s = 0; s < 64; s += 16) {
;                     PV_LOAD(bB, ev, s + 8);
;                     PV_ACC(bA, av, s);
;                     if (s + 16 < 64) PV_LOAD(bA, ev, s + 16);
;                     PV_ACC(bB, av, s + 8);
	v_cvt_scalef32_pk_f32_fp4 v[46:47], v36, 1.0
	v_pk_fma_f32 v[46:47], s[10:11], v[46:47], v[50:51] op_sel_hi:[0,1,1]
	v_cvt_scalef32_pk_f32_fp4 v[50:51], v36, 1.0 op_sel:[1,0,0]
	v_pk_fma_f32 v[50:51], s[10:11], v[50:51], v[54:55] op_sel_hi:[0,1,1]
	v_cvt_scalef32_pk_f32_fp4 v[54:55], v36, 1.0 op_sel:[0,1,0]
	v_pk_fma_f32 v[54:55], s[10:11], v[54:55], v[58:59] op_sel_hi:[0,1,1]
	v_cvt_scalef32_pk_f32_fp4 v[58:59], v36, 1.0 op_sel:[1,1,0]
	v_pk_fma_f32 v[58:59], s[10:11], v[58:59], v[62:63] op_sel_hi:[0,1,1]
	v_cvt_scalef32_pk_f32_fp4 v[62:63], v37, 1.0
	v_pk_fma_f32 v[62:63], s[10:11], v[62:63], v[66:67] op_sel_hi:[0,1,1]
	v_cvt_scalef32_pk_f32_fp4 v[66:67], v37, 1.0 op_sel:[1,0,0]
	v_pk_fma_f32 v[66:67], s[10:11], v[66:67], v[70:71] op_sel_hi:[0,1,1]
	v_cvt_scalef32_pk_f32_fp4 v[70:71], v37, 1.0 op_sel:[0,1,0]
	v_cvt_scalef32_pk_f32_fp4 v[36:37], v37, 1.0 op_sel:[1,1,0]
	v_pk_fma_f32 v[36:37], s[10:11], v[36:37], v[40:41] op_sel_hi:[0,1,1]
	v_cvt_scalef32_pk_f32_fp4 v[40:41], v38, 1.0
	v_pk_fma_f32 v[40:41], s[10:11], v[40:41], v[44:45] op_sel_hi:[0,1,1]
	v_cvt_scalef32_pk_f32_fp4 v[44:45], v38, 1.0 op_sel:[1,0,0]
	v_pk_fma_f32 v[44:45], s[10:11], v[44:45], v[48:49] op_sel_hi:[0,1,1]
	v_cvt_scalef32_pk_f32_fp4 v[48:49], v38, 1.0 op_sel:[0,1,0]
	v_pk_fma_f32 v[48:49], s[10:11], v[48:49], v[52:53] op_sel_hi:[0,1,1]
	v_cvt_scalef32_pk_f32_fp4 v[52:53], v38, 1.0 op_sel:[1,1,0]
	v_pk_fma_f32 v[52:53], s[10:11], v[52:53], v[56:57] op_sel_hi:[0,1,1]
	v_cvt_scalef32_pk_f32_fp4 v[56:57], v39, 1.0
	v_pk_fma_f32 v[56:57], s[10:11], v[56:57], v[60:61] op_sel_hi:[0,1,1]
	v_cvt_scalef32_pk_f32_fp4 v[60:61], v39, 1.0 op_sel:[1,0,0]
	v_pk_fma_f32 v[60:61], s[10:11], v[60:61], v[64:65] op_sel_hi:[0,1,1]
	v_cvt_scalef32_pk_f32_fp4 v[64:65], v39, 1.0 op_sel:[0,1,0]
	v_cvt_scalef32_pk_f32_fp4 v[38:39], v39, 1.0 op_sel:[1,1,0]
	v_pk_fma_f32 v[70:71], s[10:11], v[70:71], v[74:75] op_sel_hi:[0,1,1]
	v_pk_fma_f32 v[64:65], s[10:11], v[64:65], v[68:69] op_sel_hi:[0,1,1]
	v_pk_fma_f32 v[38:39], s[10:11], v[38:39], v[42:43] op_sel_hi:[0,1,1]
	v_readlane_b32 s10, v107, s31
	s_waitcnt vmcnt(0)
	v_mov_b64_e32 v[94:95], v[6:7]
	v_mov_b64_e32 v[90:91], v[2:3]
	v_mov_b64_e32 v[88:89], v[0:1]
	v_mov_b64_e32 v[82:83], v[14:15]
	v_mov_b64_e32 v[78:79], v[22:23]
	v_cvt_scalef32_pk_f32_fp4 v[42:43], v32, 1.0
	v_mov_b64_e32 v[80:81], v[12:13]
	v_pk_fma_f32 v[118:119], s[10:11], v[42:43], v[46:47] op_sel_hi:[0,1,1]
	v_cvt_scalef32_pk_f32_fp4 v[42:43], v32, 1.0 op_sel:[1,0,0]
	v_pk_fma_f32 v[122:123], s[10:11], v[42:43], v[50:51] op_sel_hi:[0,1,1]
	v_cvt_scalef32_pk_f32_fp4 v[42:43], v32, 1.0 op_sel:[0,1,0]
	v_pk_fma_f32 v[144:145], s[10:11], v[42:43], v[54:55] op_sel_hi:[0,1,1]
	v_cvt_scalef32_pk_f32_fp4 v[42:43], v32, 1.0 op_sel:[1,1,0]
	v_pk_fma_f32 v[142:143], s[10:11], v[42:43], v[58:59] op_sel_hi:[0,1,1]
	v_cvt_scalef32_pk_f32_fp4 v[42:43], v33, 1.0
	v_pk_fma_f32 v[140:141], s[10:11], v[42:43], v[62:63] op_sel_hi:[0,1,1]
	v_cvt_scalef32_pk_f32_fp4 v[42:43], v33, 1.0 op_sel:[1,0,0]
	v_pk_fma_f32 v[138:139], s[10:11], v[42:43], v[66:67] op_sel_hi:[0,1,1]
	v_cvt_scalef32_pk_f32_fp4 v[42:43], v33, 1.0 op_sel:[0,1,0]
	v_cvt_scalef32_pk_f32_fp4 v[32:33], v33, 1.0 op_sel:[1,1,0]
	v_pk_fma_f32 v[132:133], s[10:11], v[32:33], v[36:37] op_sel_hi:[0,1,1]
	v_cvt_scalef32_pk_f32_fp4 v[32:33], v34, 1.0
	v_pk_fma_f32 v[130:131], s[10:11], v[32:33], v[40:41] op_sel_hi:[0,1,1]
	v_cvt_scalef32_pk_f32_fp4 v[32:33], v34, 1.0 op_sel:[1,0,0]
	v_pk_fma_f32 v[126:127], s[10:11], v[32:33], v[44:45] op_sel_hi:[0,1,1]
	v_cvt_scalef32_pk_f32_fp4 v[32:33], v34, 1.0 op_sel:[0,1,0]
	v_pk_fma_f32 v[124:125], s[10:11], v[32:33], v[48:49] op_sel_hi:[0,1,1]
	v_cvt_scalef32_pk_f32_fp4 v[32:33], v34, 1.0 op_sel:[1,1,0]
	v_pk_fma_f32 v[120:121], s[10:11], v[32:33], v[52:53] op_sel_hi:[0,1,1]
	v_cvt_scalef32_pk_f32_fp4 v[32:33], v35, 1.0
	v_pk_fma_f32 v[116:117], s[10:11], v[32:33], v[56:57] op_sel_hi:[0,1,1]
	v_cvt_scalef32_pk_f32_fp4 v[32:33], v35, 1.0 op_sel:[1,0,0]
	v_pk_fma_f32 v[114:115], s[10:11], v[32:33], v[60:61] op_sel_hi:[0,1,1]
	v_cvt_scalef32_pk_f32_fp4 v[32:33], v35, 1.0 op_sel:[0,1,0]
	v_pk_fma_f32 v[134:135], s[10:11], v[42:43], v[70:71] op_sel_hi:[0,1,1]
	v_pk_fma_f32 v[112:113], s[10:11], v[32:33], v[64:65] op_sel_hi:[0,1,1]
	v_cvt_scalef32_pk_f32_fp4 v[32:33], v35, 1.0 op_sel:[1,1,0]
	v_mov_b64_e32 v[42:43], v[26:27]
	v_mov_b64_e32 v[70:71], v[10:11]
	v_mov_b64_e32 v[50:51], v[30:31]
	v_mov_b64_e32 v[62:63], v[18:19]
	v_pk_fma_f32 v[110:111], s[10:11], v[32:33], v[38:39] op_sel_hi:[0,1,1]
	v_mov_b64_e32 v[40:41], v[24:25]
	v_mov_b64_e32 v[68:69], v[8:9]
	v_mov_b64_e32 v[48:49], v[28:29]
	v_mov_b64_e32 v[60:61], v[16:17]
	v_mov_b64_e32 v[76:77], v[20:21]
	v_mov_b64_e32 v[92:93], v[4:5]
	s_cbranch_vccz .LBB0_885
